# input loads (x rows, f32 weights) with sc1 nt instead of nt
# baseline (speedup 1.0000x reference)
.LBB0_15:
	s_cmpk_gt_i32 s29, 0x5ff
	s_mov_b64 s[2:3], -1
	s_cbranch_scc0 .LBB0_93
	s_cmpk_gt_u32 s29, 0x7ff
	s_cbranch_scc0 .LBB0_90
	s_cmpk_gt_u32 s29, 0xfff
	s_cbranch_scc0 .LBB0_23
	s_cmpk_gt_u32 s29, 0x17ff
	s_cbranch_scc0 .LBB0_20
	s_add_i32 s0, s29, 0xe800
	s_and_b32 s2, s0, 0xffff
	s_mul_i32 s2, s2, 0xaaab
	s_lshr_b32 s2, s2, 21
	s_mul_i32 s3, s2, 48
	s_sub_i32 s0, s0, s3
	s_and_b32 s3, s0, 0xffff
	s_lshl_b32 s0, s3, 7
	v_lshl_or_b32 v0, s2, 6, v28
	v_lshl_add_u64 v[22:23], v[12:13], 0, s[0:1]
	v_mad_u64_u32 v[24:25], s[4:5], v0, s27, v[22:23]
	global_load_dword v26, v[24:25], off sc1 nt
	v_lshlrev_b32_e32 v24, 2, v0
	v_or_b32_e32 v73, 2, v0
	global_load_dword v27, v24, s[12:13]
	v_mad_u64_u32 v[24:25], s[4:5], v73, s27, v[22:23]
	global_load_dword v74, v[24:25], off sc1 nt
	v_lshlrev_b32_e32 v24, 2, v73
	v_or_b32_e32 v75, 4, v0
	global_load_dword v73, v24, s[12:13]
	v_mad_u64_u32 v[24:25], s[4:5], v75, s27, v[22:23]
	global_load_dword v76, v[24:25], off sc1 nt
	v_lshlrev_b32_e32 v24, 2, v75
	v_or_b32_e32 v77, 6, v0
	global_load_dword v75, v24, s[12:13]
	v_mad_u64_u32 v[24:25], s[4:5], v77, s27, v[22:23]
	global_load_dword v78, v[24:25], off sc1 nt
	v_lshlrev_b32_e32 v24, 2, v77
	v_or_b32_e32 v79, 8, v0
	global_load_dword v77, v24, s[12:13]
	v_mad_u64_u32 v[24:25], s[4:5], v79, s27, v[22:23]
	global_load_dword v80, v[24:25], off sc1 nt
	v_lshlrev_b32_e32 v24, 2, v79
	v_or_b32_e32 v81, 10, v0
	global_load_dword v79, v24, s[12:13]
	v_mad_u64_u32 v[24:25], s[4:5], v81, s27, v[22:23]
	global_load_dword v82, v[24:25], off sc1 nt
	v_lshlrev_b32_e32 v24, 2, v81
	v_or_b32_e32 v83, 12, v0
	global_load_dword v81, v24, s[12:13]
	v_mad_u64_u32 v[24:25], s[4:5], v83, s27, v[22:23]
	global_load_dword v84, v[24:25], off sc1 nt
	v_lshlrev_b32_e32 v24, 2, v83
	v_or_b32_e32 v85, 14, v0
	global_load_dword v83, v24, s[12:13]
	v_mad_u64_u32 v[24:25], s[4:5], v85, s27, v[22:23]
	global_load_dword v86, v[24:25], off sc1 nt
	v_lshlrev_b32_e32 v24, 2, v85
	v_or_b32_e32 v87, 16, v0
	global_load_dword v85, v24, s[12:13]
	v_mad_u64_u32 v[24:25], s[4:5], v87, s27, v[22:23]
	global_load_dword v88, v[24:25], off sc1 nt
	v_lshlrev_b32_e32 v24, 2, v87
	v_or_b32_e32 v89, 18, v0
	global_load_dword v87, v24, s[12:13]
	v_mad_u64_u32 v[24:25], s[4:5], v89, s27, v[22:23]
	global_load_dword v90, v[24:25], off sc1 nt
	v_lshlrev_b32_e32 v24, 2, v89
	v_or_b32_e32 v91, 20, v0
	global_load_dword v89, v24, s[12:13]
	v_mad_u64_u32 v[24:25], s[4:5], v91, s27, v[22:23]
	global_load_dword v92, v[24:25], off sc1 nt
	v_lshlrev_b32_e32 v24, 2, v91
	v_or_b32_e32 v93, 22, v0
	global_load_dword v91, v24, s[12:13]
	v_mad_u64_u32 v[24:25], s[4:5], v93, s27, v[22:23]
	global_load_dword v94, v[24:25], off sc1 nt
	v_lshlrev_b32_e32 v24, 2, v93
	v_or_b32_e32 v95, 24, v0
	global_load_dword v93, v24, s[12:13]
	v_mad_u64_u32 v[24:25], s[4:5], v95, s27, v[22:23]
	global_load_dword v96, v[24:25], off sc1 nt
	v_lshlrev_b32_e32 v24, 2, v95
	v_or_b32_e32 v97, 26, v0
	global_load_dword v95, v24, s[12:13]
	v_mad_u64_u32 v[24:25], s[4:5], v97, s27, v[22:23]
	global_load_dword v98, v[24:25], off sc1 nt
	v_lshlrev_b32_e32 v24, 2, v97
	v_or_b32_e32 v99, 28, v0
	global_load_dword v97, v24, s[12:13]
	v_mad_u64_u32 v[24:25], s[4:5], v99, s27, v[22:23]
	global_load_dword v100, v[24:25], off sc1 nt
	v_lshlrev_b32_e32 v24, 2, v99
	v_or_b32_e32 v101, 30, v0
	global_load_dword v99, v24, s[12:13]
	v_mad_u64_u32 v[24:25], s[4:5], v101, s27, v[22:23]
	global_load_dword v102, v[24:25], off sc1 nt
	v_lshlrev_b32_e32 v24, 2, v101
	v_or_b32_e32 v103, 32, v0
	global_load_dword v101, v24, s[12:13]
	v_mad_u64_u32 v[24:25], s[4:5], v103, s27, v[22:23]
	global_load_dword v104, v[24:25], off sc1 nt
	v_lshlrev_b32_e32 v24, 2, v103
	v_or_b32_e32 v105, 34, v0
	global_load_dword v103, v24, s[12:13]
	v_mad_u64_u32 v[24:25], s[4:5], v105, s27, v[22:23]
	global_load_dword v106, v[24:25], off sc1 nt
	v_lshlrev_b32_e32 v24, 2, v105
	v_or_b32_e32 v107, 36, v0
	global_load_dword v105, v24, s[12:13]
	v_mad_u64_u32 v[24:25], s[4:5], v107, s27, v[22:23]
	global_load_dword v108, v[24:25], off sc1 nt
	v_lshlrev_b32_e32 v24, 2, v107
	v_or_b32_e32 v109, 38, v0
	global_load_dword v107, v24, s[12:13]
	v_mad_u64_u32 v[24:25], s[4:5], v109, s27, v[22:23]
	global_load_dword v110, v[24:25], off sc1 nt
	v_lshlrev_b32_e32 v24, 2, v109
	v_or_b32_e32 v111, 40, v0
	global_load_dword v109, v24, s[12:13]
	v_mad_u64_u32 v[24:25], s[4:5], v111, s27, v[22:23]
	global_load_dword v112, v[24:25], off sc1 nt
	v_lshlrev_b32_e32 v24, 2, v111
	v_or_b32_e32 v113, 42, v0
	global_load_dword v111, v24, s[12:13]
	v_mad_u64_u32 v[24:25], s[4:5], v113, s27, v[22:23]
	global_load_dword v114, v[24:25], off sc1 nt
	v_lshlrev_b32_e32 v24, 2, v113
	v_or_b32_e32 v115, 44, v0
	global_load_dword v113, v24, s[12:13]
	v_mad_u64_u32 v[24:25], s[4:5], v115, s27, v[22:23]
	global_load_dword v116, v[24:25], off sc1 nt
	v_lshlrev_b32_e32 v24, 2, v115
	v_or_b32_e32 v117, 46, v0
	global_load_dword v115, v24, s[12:13]
	v_mad_u64_u32 v[24:25], s[4:5], v117, s27, v[22:23]
	global_load_dword v118, v[24:25], off sc1 nt
	v_lshlrev_b32_e32 v24, 2, v117
	v_or_b32_e32 v119, 48, v0
	global_load_dword v117, v24, s[12:13]
	v_mad_u64_u32 v[24:25], s[4:5], v119, s27, v[22:23]
	global_load_dword v120, v[24:25], off sc1 nt
	v_lshlrev_b32_e32 v24, 2, v119
	v_or_b32_e32 v121, 50, v0
	global_load_dword v119, v24, s[12:13]
	v_mad_u64_u32 v[24:25], s[4:5], v121, s27, v[22:23]
	global_load_dword v122, v[24:25], off sc1 nt
	v_lshlrev_b32_e32 v24, 2, v121
	v_or_b32_e32 v123, 52, v0
	global_load_dword v121, v24, s[12:13]
	v_mad_u64_u32 v[24:25], s[4:5], v123, s27, v[22:23]
	global_load_dword v124, v[24:25], off sc1 nt
	v_lshlrev_b32_e32 v24, 2, v123
	v_or_b32_e32 v125, 54, v0
	global_load_dword v123, v24, s[12:13]
	v_mad_u64_u32 v[24:25], s[4:5], v125, s27, v[22:23]
	global_load_dword v126, v[24:25], off sc1 nt
	v_lshlrev_b32_e32 v24, 2, v125
	v_or_b32_e32 v127, 56, v0
	global_load_dword v125, v24, s[12:13]
	v_mad_u64_u32 v[24:25], s[4:5], v127, s27, v[22:23]
	global_load_dword v128, v[24:25], off sc1 nt
	v_lshlrev_b32_e32 v24, 2, v127
	v_or_b32_e32 v129, 58, v0
	global_load_dword v127, v24, s[12:13]
	v_mad_u64_u32 v[24:25], s[4:5], v129, s27, v[22:23]
	global_load_dword v130, v[24:25], off sc1 nt
	v_lshlrev_b32_e32 v24, 2, v129
	v_or_b32_e32 v131, 60, v0
	v_or_b32_e32 v0, 62, v0
	global_load_dword v129, v24, s[12:13]
	v_mad_u64_u32 v[24:25], s[4:5], v131, s27, v[22:23]
	v_mad_u64_u32 v[22:23], s[4:5], v0, s27, v[22:23]
	global_load_dword v24, v[24:25], off sc1 nt
	v_lshlrev_b32_e32 v0, 2, v0
	global_load_dword v22, v[22:23], off sc1 nt
	v_lshlrev_b32_e32 v25, 2, v131
	global_load_dword v25, v25, s[12:13]
	s_waitcnt vmcnt(61)
	v_mul_f32_e32 v23, v26, v27
	global_load_dword v0, v0, s[12:13]
	s_waitcnt vmcnt(60)
	v_mul_f32_e32 v26, v74, v73
	ds_write2_b32 v29, v23, v26 offset1:66
	s_waitcnt vmcnt(58)
	v_mul_f32_e32 v23, v76, v75
	s_waitcnt vmcnt(56)
	v_mul_f32_e32 v26, v78, v77
	ds_write2_b32 v29, v23, v26 offset0:132 offset1:198
	s_waitcnt vmcnt(54)
	v_mul_f32_e32 v23, v80, v79
	s_waitcnt vmcnt(52)
	v_mul_f32_e32 v26, v82, v81
	ds_write2_b32 v35, v23, v26 offset0:8 offset1:74
	s_waitcnt vmcnt(50)
	v_mul_f32_e32 v23, v84, v83
	s_waitcnt vmcnt(48)
	v_mul_f32_e32 v26, v86, v85
	ds_write2_b32 v35, v23, v26 offset0:140 offset1:206
	s_waitcnt vmcnt(46)
	v_mul_f32_e32 v23, v88, v87
	s_waitcnt vmcnt(44)
	v_mul_f32_e32 v26, v90, v89
	ds_write2_b32 v36, v23, v26 offset0:16 offset1:82
	s_waitcnt vmcnt(42)
	v_mul_f32_e32 v23, v92, v91
	s_waitcnt vmcnt(40)
	v_mul_f32_e32 v26, v94, v93
	ds_write2_b32 v36, v23, v26 offset0:148 offset1:214
	s_waitcnt vmcnt(38)
	v_mul_f32_e32 v23, v96, v95
	s_waitcnt vmcnt(36)
	v_mul_f32_e32 v26, v98, v97
	ds_write2_b32 v37, v23, v26 offset0:24 offset1:90
	s_waitcnt vmcnt(34)
	v_mul_f32_e32 v23, v100, v99
	s_waitcnt vmcnt(32)
	v_mul_f32_e32 v26, v102, v101
	ds_write2_b32 v37, v23, v26 offset0:156 offset1:222
	s_waitcnt vmcnt(30)
	v_mul_f32_e32 v23, v104, v103
	s_waitcnt vmcnt(28)
	v_mul_f32_e32 v26, v106, v105
	ds_write2_b32 v38, v23, v26 offset0:32 offset1:98
	s_waitcnt vmcnt(26)
	v_mul_f32_e32 v23, v108, v107
	s_waitcnt vmcnt(24)
	v_mul_f32_e32 v26, v110, v109
	ds_write2_b32 v38, v23, v26 offset0:164 offset1:230
	s_waitcnt vmcnt(22)
	v_mul_f32_e32 v23, v112, v111
	s_waitcnt vmcnt(20)
	v_mul_f32_e32 v26, v114, v113
	ds_write2_b32 v39, v23, v26 offset0:40 offset1:106
	s_waitcnt vmcnt(18)
	v_mul_f32_e32 v23, v116, v115
	s_waitcnt vmcnt(16)
	v_mul_f32_e32 v26, v118, v117
	ds_write2_b32 v39, v23, v26 offset0:172 offset1:238
	s_lshl_b32 s4, s3, 5
	s_and_b32 s4, s4, 0x700
	s_waitcnt vmcnt(14)
	v_mul_f32_e32 v23, v120, v119
	s_and_b32 s0, s0, 0x80
	s_lshl_b32 s3, s3, 4
	s_or_b32 s0, s4, s0
	s_and_b32 s3, s3, 0x60
	s_or_b32 s3, s0, s3
	s_waitcnt vmcnt(12)
	v_mul_f32_e32 v26, v122, v121
	ds_write2_b32 v40, v23, v26 offset0:48 offset1:114
	s_lshl_b32 s0, s2, 7
	v_lshl_add_u64 v[88:89], v[2:3], 0, s[0:1]
	s_waitcnt vmcnt(10)
	v_mul_f32_e32 v23, v124, v123
	s_waitcnt vmcnt(8)
	v_mul_f32_e32 v26, v126, v125
	ds_write2_b32 v40, v23, v26 offset0:180 offset1:246
	s_waitcnt vmcnt(6)
	v_mul_f32_e32 v23, v128, v127
	s_waitcnt vmcnt(4)
	v_mul_f32_e32 v26, v130, v129
	ds_write2_b32 v41, v23, v26 offset0:56 offset1:122
	s_waitcnt vmcnt(1)
	v_mul_f32_e32 v23, v24, v25
	s_waitcnt vmcnt(0)
	v_mul_f32_e32 v0, v22, v0
	ds_write2_b32 v41, v23, v0 offset0:188 offset1:254
	s_waitcnt lgkmcnt(0)
	ds_read2_b32 v[26:27], v31 offset0:33 offset1:41
	ds_read2_b32 v[74:75], v31 offset1:8
	ds_read2_b32 v[76:77], v31 offset0:66 offset1:74
	ds_read2_b32 v[78:79], v31 offset0:99 offset1:107
	ds_read2_b32 v[80:81], v31 offset0:132 offset1:140
	ds_read2_b32 v[82:83], v31 offset0:165 offset1:173
	ds_read2_b32 v[84:85], v31 offset0:198 offset1:206
	ds_read2_b32 v[86:87], v31 offset0:231 offset1:239
	v_or_b32_e32 v0, s3, v30
	v_lshlrev_b32_e32 v0, 11, v0
	s_waitcnt lgkmcnt(6)
	v_cvt_pk_bf16_f32 v22, v74, v26
	s_waitcnt lgkmcnt(4)
	v_cvt_pk_bf16_f32 v23, v76, v78
	s_waitcnt lgkmcnt(2)
	v_cvt_pk_bf16_f32 v24, v80, v82
	s_waitcnt lgkmcnt(0)
	v_cvt_pk_bf16_f32 v25, v84, v86
	v_lshl_add_u64 v[90:91], v[88:89], 0, v[0:1]
	global_store_dwordx4 v[90:91], v[22:25], off
	v_or_b32_e32 v0, s3, v32
	v_lshlrev_b32_e32 v0, 11, v0
	v_cvt_pk_bf16_f32 v22, v75, v27
	v_cvt_pk_bf16_f32 v23, v77, v79
	v_cvt_pk_bf16_f32 v24, v81, v83
	v_cvt_pk_bf16_f32 v25, v85, v87
	ds_read2_b32 v[74:75], v31 offset0:49 offset1:57
	ds_read2_b32 v[76:77], v31 offset0:16 offset1:24
	ds_read2_b32 v[78:79], v31 offset0:82 offset1:90
	ds_read2_b32 v[80:81], v31 offset0:115 offset1:123
	ds_read2_b32 v[82:83], v31 offset0:148 offset1:156
	ds_read2_b32 v[84:85], v31 offset0:181 offset1:189
	ds_read2_b32 v[86:87], v31 offset0:214 offset1:222
	ds_read2_b32 v[90:91], v31 offset0:247 offset1:255
	v_lshl_add_u64 v[26:27], v[88:89], 0, v[0:1]
	v_or_b32_e32 v0, s3, v33
	v_lshlrev_b32_e32 v0, 11, v0
	global_store_dwordx4 v[26:27], v[22:25], off
	v_lshl_add_u64 v[26:27], v[88:89], 0, v[0:1]
	v_or_b32_e32 v0, s3, v34
	s_waitcnt lgkmcnt(6)
	v_cvt_pk_bf16_f32 v22, v76, v74
	s_waitcnt lgkmcnt(4)
	v_cvt_pk_bf16_f32 v23, v78, v80
	s_waitcnt lgkmcnt(2)
	v_cvt_pk_bf16_f32 v24, v82, v84
	s_waitcnt lgkmcnt(0)
	v_cvt_pk_bf16_f32 v25, v86, v90
	v_lshlrev_b32_e32 v0, 11, v0
	global_store_dwordx4 v[26:27], v[22:25], off
	v_lshl_add_u64 v[26:27], v[88:89], 0, v[0:1]
	s_mov_b64 s[2:3], 0
	v_cvt_pk_bf16_f32 v22, v77, v75
	v_cvt_pk_bf16_f32 v23, v79, v81
	v_cvt_pk_bf16_f32 v24, v83, v85
	v_cvt_pk_bf16_f32 v25, v87, v91
	global_store_dwordx4 v[26:27], v[22:25], off
	s_waitcnt lgkmcnt(0)
.LBB0_20:
	s_andn2_b64 vcc, exec, s[2:3]
	s_cbranch_vccnz .LBB0_22
	s_and_b32 s3, s25, 0x1ffc0
	s_and_b32 s2, s9, 0x3e0
	v_or_b32_e32 v0, s3, v28
	s_lshl_b32 s0, s2, 2
	v_lshl_add_u64 v[22:23], v[14:15], 0, s[0:1]
	v_lshlrev_b32_e32 v0, 12, v0
	v_lshl_add_u64 v[22:23], v[22:23], 0, v[0:1]
	v_add_co_u32_e32 v24, vcc, 0x2000, v22
	s_lshl_b32 s0, s3, 1
	s_nop 0
	v_addc_co_u32_e32 v25, vcc, 0, v23, vcc
	v_add_co_u32_e32 v26, vcc, 0x4000, v22
	s_nop 1
	v_addc_co_u32_e32 v27, vcc, 0, v23, vcc
	v_add_co_u32_e32 v74, vcc, 0x6000, v22
	s_nop 1
	v_addc_co_u32_e32 v75, vcc, 0, v23, vcc
	v_add_co_u32_e32 v76, vcc, 0x8000, v22
	s_nop 1
	v_addc_co_u32_e32 v77, vcc, 0, v23, vcc
	v_add_co_u32_e32 v78, vcc, 0xa000, v22
	s_nop 1
	v_addc_co_u32_e32 v79, vcc, 0, v23, vcc
	v_add_co_u32_e32 v80, vcc, 0xc000, v22
	s_nop 1
	v_addc_co_u32_e32 v81, vcc, 0, v23, vcc
	v_add_co_u32_e32 v82, vcc, 0xe000, v22
	s_nop 1
	v_addc_co_u32_e32 v83, vcc, 0, v23, vcc
	global_load_dword v0, v[22:23], off sc1 nt
	global_load_dword v73, v[24:25], off sc1 nt
	global_load_dword v86, v[26:27], off sc1 nt
	global_load_dword v87, v[74:75], off sc1 nt
	global_load_dword v88, v[76:77], off sc1 nt
	global_load_dword v89, v[78:79], off sc1 nt
	global_load_dword v90, v[80:81], off sc1 nt
	global_load_dword v91, v[82:83], off sc1 nt
	v_add_co_u32_e32 v24, vcc, 0x10000, v22
	s_nop 1
	v_addc_co_u32_e32 v25, vcc, 0, v23, vcc
	v_add_co_u32_e32 v26, vcc, 0x12000, v22
	s_nop 1
	v_addc_co_u32_e32 v27, vcc, 0, v23, vcc
	v_add_co_u32_e32 v74, vcc, 0x14000, v22
	s_nop 1
	v_addc_co_u32_e32 v75, vcc, 0, v23, vcc
	v_add_co_u32_e32 v76, vcc, 0x16000, v22
	s_nop 1
	v_addc_co_u32_e32 v77, vcc, 0, v23, vcc
	v_add_co_u32_e32 v78, vcc, 0x18000, v22
	s_nop 1
	v_addc_co_u32_e32 v79, vcc, 0, v23, vcc
	v_add_co_u32_e32 v80, vcc, 0x1a000, v22
	s_nop 1
	v_addc_co_u32_e32 v81, vcc, 0, v23, vcc
	v_add_co_u32_e32 v82, vcc, 0x1c000, v22
	s_nop 1
	v_addc_co_u32_e32 v83, vcc, 0, v23, vcc
	v_add_co_u32_e32 v84, vcc, s24, v22
	s_nop 1
	v_addc_co_u32_e32 v85, vcc, 0, v23, vcc
	global_load_dword v92, v[24:25], off sc1 nt
	global_load_dword v93, v[26:27], off sc1 nt
	global_load_dword v94, v[74:75], off sc1 nt
	global_load_dword v95, v[76:77], off sc1 nt
	global_load_dword v96, v[78:79], off sc1 nt
	global_load_dword v97, v[80:81], off sc1 nt
	global_load_dword v98, v[82:83], off sc1 nt
	global_load_dword v99, v[84:85], off sc1 nt
	v_add_co_u32_e32 v24, vcc, 0x20000, v22
	s_nop 1
	v_addc_co_u32_e32 v25, vcc, 0, v23, vcc
	v_add_co_u32_e32 v26, vcc, 0x22000, v22
	s_nop 1
	v_addc_co_u32_e32 v27, vcc, 0, v23, vcc
	v_add_co_u32_e32 v74, vcc, 0x24000, v22
	s_nop 1
	v_addc_co_u32_e32 v75, vcc, 0, v23, vcc
	v_add_co_u32_e32 v76, vcc, 0x26000, v22
	s_nop 1
	v_addc_co_u32_e32 v77, vcc, 0, v23, vcc
	v_add_co_u32_e32 v78, vcc, 0x28000, v22
	s_nop 1
	v_addc_co_u32_e32 v79, vcc, 0, v23, vcc
	v_add_co_u32_e32 v80, vcc, 0x2a000, v22
	s_nop 1
	v_addc_co_u32_e32 v81, vcc, 0, v23, vcc
	v_add_co_u32_e32 v82, vcc, 0x2c000, v22
	s_nop 1
	v_addc_co_u32_e32 v83, vcc, 0, v23, vcc
	v_add_co_u32_e32 v84, vcc, 0x2e000, v22
	s_nop 1
	v_addc_co_u32_e32 v85, vcc, 0, v23, vcc
	global_load_dword v100, v[24:25], off sc1 nt
	global_load_dword v101, v[26:27], off sc1 nt
	global_load_dword v102, v[74:75], off sc1 nt
	global_load_dword v103, v[76:77], off sc1 nt
	global_load_dword v104, v[78:79], off sc1 nt
	global_load_dword v105, v[80:81], off sc1 nt
	global_load_dword v106, v[82:83], off sc1 nt
	s_nop 0
	global_load_dword v84, v[84:85], off sc1 nt
	v_add_co_u32_e32 v24, vcc, 0x30000, v22
	s_nop 1
	v_addc_co_u32_e32 v25, vcc, 0, v23, vcc
	v_add_co_u32_e32 v26, vcc, 0x32000, v22
	s_nop 1
	v_addc_co_u32_e32 v27, vcc, 0, v23, vcc
	v_add_co_u32_e32 v74, vcc, 0x34000, v22
	s_nop 1
	v_addc_co_u32_e32 v75, vcc, 0, v23, vcc
	v_add_co_u32_e32 v76, vcc, 0x36000, v22
	s_nop 1
	v_addc_co_u32_e32 v77, vcc, 0, v23, vcc
	v_add_co_u32_e32 v78, vcc, 0x38000, v22
	s_nop 1
	v_addc_co_u32_e32 v79, vcc, 0, v23, vcc
	v_add_co_u32_e32 v80, vcc, 0x3a000, v22
	s_nop 1
	v_addc_co_u32_e32 v81, vcc, 0, v23, vcc
	v_add_co_u32_e32 v82, vcc, 0x3c000, v22
	s_nop 1
	v_addc_co_u32_e32 v83, vcc, 0, v23, vcc
	v_add_co_u32_e32 v22, vcc, 0x3e000, v22
	s_nop 1
	v_addc_co_u32_e32 v23, vcc, 0, v23, vcc
	global_load_dword v24, v[24:25], off sc1 nt
	s_nop 0
	global_load_dword v25, v[26:27], off sc1 nt
	s_nop 0
	global_load_dword v26, v[74:75], off sc1 nt
	global_load_dword v27, v[76:77], off sc1 nt
	s_nop 0
	global_load_dword v74, v[78:79], off sc1 nt
	global_load_dword v75, v[80:81], off sc1 nt
	global_load_dword v76, v[82:83], off sc1 nt
	s_nop 0
	global_load_dword v22, v[22:23], off sc1 nt
	s_waitcnt vmcnt(30)
	ds_write2_b32 v29, v0, v73 offset1:66
	s_waitcnt vmcnt(28)
	ds_write2_b32 v29, v86, v87 offset0:132 offset1:198
	s_waitcnt vmcnt(26)
	ds_write2_b32 v35, v88, v89 offset0:8 offset1:74
	s_waitcnt vmcnt(24)
	ds_write2_b32 v35, v90, v91 offset0:140 offset1:206
	s_waitcnt vmcnt(22)
	ds_write2_b32 v36, v92, v93 offset0:16 offset1:82
	s_waitcnt vmcnt(20)
	ds_write2_b32 v36, v94, v95 offset0:148 offset1:214
	s_waitcnt vmcnt(18)
	ds_write2_b32 v37, v96, v97 offset0:24 offset1:90
	s_waitcnt vmcnt(16)
	ds_write2_b32 v37, v98, v99 offset0:156 offset1:222
	s_waitcnt vmcnt(14)
	ds_write2_b32 v38, v100, v101 offset0:32 offset1:98
	s_waitcnt vmcnt(12)
	ds_write2_b32 v38, v102, v103 offset0:164 offset1:230
	s_waitcnt vmcnt(10)
	ds_write2_b32 v39, v104, v105 offset0:40 offset1:106
	s_waitcnt vmcnt(8)
	ds_write2_b32 v39, v106, v84 offset0:172 offset1:238
	s_waitcnt vmcnt(6)
	ds_write2_b32 v40, v24, v25 offset0:48 offset1:114
	s_waitcnt vmcnt(4)
	ds_write2_b32 v40, v26, v27 offset0:180 offset1:246
	s_waitcnt vmcnt(2)
	ds_write2_b32 v41, v74, v75 offset0:56 offset1:122
	s_waitcnt vmcnt(0)
	ds_write2_b32 v41, v76, v22 offset0:188 offset1:254
	s_waitcnt lgkmcnt(0)
	ds_read2_b32 v[26:27], v31 offset0:33 offset1:41
	ds_read2_b32 v[74:75], v31 offset1:8
	ds_read2_b32 v[76:77], v31 offset0:66 offset1:74
	ds_read2_b32 v[78:79], v31 offset0:99 offset1:107
	ds_read2_b32 v[80:81], v31 offset0:132 offset1:140
	ds_read2_b32 v[82:83], v31 offset0:165 offset1:173
	ds_read2_b32 v[84:85], v31 offset0:198 offset1:206
	ds_read2_b32 v[86:87], v31 offset0:231 offset1:239
	v_or_b32_e32 v0, s2, v30
	v_lshl_add_u64 v[88:89], v[4:5], 0, s[0:1]
	v_lshlrev_b32_e32 v0, 13, v0
	s_waitcnt lgkmcnt(6)
	v_cvt_pk_bf16_f32 v22, v74, v26
	s_waitcnt lgkmcnt(4)
	v_cvt_pk_bf16_f32 v23, v76, v78
	s_waitcnt lgkmcnt(2)
	v_cvt_pk_bf16_f32 v24, v80, v82
	s_waitcnt lgkmcnt(0)
	v_cvt_pk_bf16_f32 v25, v84, v86
	v_lshl_add_u64 v[90:91], v[88:89], 0, v[0:1]
	global_store_dwordx4 v[90:91], v[22:25], off
	v_or_b32_e32 v0, s2, v32
	v_lshlrev_b32_e32 v0, 13, v0
	v_cvt_pk_bf16_f32 v22, v75, v27
	v_cvt_pk_bf16_f32 v23, v77, v79
	v_cvt_pk_bf16_f32 v24, v81, v83
	v_cvt_pk_bf16_f32 v25, v85, v87
	ds_read2_b32 v[74:75], v31 offset0:49 offset1:57
	ds_read2_b32 v[76:77], v31 offset0:16 offset1:24
	ds_read2_b32 v[78:79], v31 offset0:82 offset1:90
	ds_read2_b32 v[80:81], v31 offset0:115 offset1:123
	ds_read2_b32 v[82:83], v31 offset0:148 offset1:156
	ds_read2_b32 v[84:85], v31 offset0:181 offset1:189
	ds_read2_b32 v[86:87], v31 offset0:214 offset1:222
	ds_read2_b32 v[90:91], v31 offset0:247 offset1:255
	v_lshl_add_u64 v[26:27], v[88:89], 0, v[0:1]
	v_or_b32_e32 v0, s2, v33
	v_lshlrev_b32_e32 v0, 13, v0
	global_store_dwordx4 v[26:27], v[22:25], off
	v_lshl_add_u64 v[26:27], v[88:89], 0, v[0:1]
	v_or_b32_e32 v0, s2, v34
	s_waitcnt lgkmcnt(6)
	v_cvt_pk_bf16_f32 v22, v76, v74
	s_waitcnt lgkmcnt(4)
	v_cvt_pk_bf16_f32 v23, v78, v80
	s_waitcnt lgkmcnt(2)
	v_cvt_pk_bf16_f32 v24, v82, v84
	s_waitcnt lgkmcnt(0)
	v_cvt_pk_bf16_f32 v25, v86, v90
	v_lshlrev_b32_e32 v0, 13, v0
	global_store_dwordx4 v[26:27], v[22:25], off
	v_lshl_add_u64 v[26:27], v[88:89], 0, v[0:1]
	s_nop 0
	v_cvt_pk_bf16_f32 v22, v77, v75
	v_cvt_pk_bf16_f32 v23, v79, v81
	v_cvt_pk_bf16_f32 v24, v83, v85
	v_cvt_pk_bf16_f32 v25, v87, v91
	global_store_dwordx4 v[26:27], v[22:25], off
	s_waitcnt lgkmcnt(0)

.LBB0_23:
	s_andn2_b64 vcc, exec, s[2:3]
	s_cbranch_vccnz .LBB0_89
	s_add_i32 s0, s29, 0xf800
	s_lshr_b32 s0, s0, 1
	s_and_b32 s3, s0, 0x7fc0
	s_and_b32 s2, s9, 0xfe0
	v_or_b32_e32 v27, s3, v28
	s_lshl_b32 s0, s2, 2
	v_lshl_add_u64 v[22:23], v[16:17], 0, s[0:1]
	v_lshlrev_b32_e32 v0, 14, v27
	v_lshl_add_u64 v[24:25], v[22:23], 0, v[0:1]
	global_load_dword v24, v[24:25], off sc1 nt
	v_cndmask_b32_e64 v0, 0, 1, s[14:15]
	v_mov_b32_e32 v26, 1.0
	v_cmp_ne_u32_e64 s[4:5], 1, v0
	s_andn2_b64 vcc, exec, s[14:15]
	v_lshlrev_b32_e32 v25, 2, v27
	v_mov_b32_e32 v73, 1.0
	s_cbranch_vccnz .LBB0_26
	v_readlane_b32 s36, v254, 13
	v_readlane_b32 s42, v254, 19
	v_readlane_b32 s43, v254, 20
	v_readlane_b32 s37, v254, 14
	v_readlane_b32 s38, v254, 15
	v_readlane_b32 s39, v254, 16
	v_readlane_b32 s40, v254, 17
	v_readlane_b32 s41, v254, 18
	global_load_dword v73, v25, s[42:43]
	v_readlane_b32 s44, v254, 21
	v_readlane_b32 s45, v254, 22
	v_readlane_b32 s46, v254, 23
	v_readlane_b32 s47, v254, 24
	v_readlane_b32 s48, v254, 25
	v_readlane_b32 s49, v254, 26
	v_readlane_b32 s50, v254, 27
	v_readlane_b32 s51, v254, 28
.LBB0_26:
	v_lshl_or_b32 v0, v27, 14, v42
	v_lshl_add_u64 v[74:75], v[22:23], 0, v[0:1]
	global_load_dword v74, v[74:75], off sc1 nt
	s_and_b64 vcc, exec, s[4:5]
	s_cbranch_vccnz .LBB0_28
	v_readlane_b32 s36, v254, 13
	v_readlane_b32 s42, v254, 19
	v_readlane_b32 s43, v254, 20
	v_readlane_b32 s37, v254, 14
	v_readlane_b32 s38, v254, 15
	v_readlane_b32 s39, v254, 16
	v_readlane_b32 s40, v254, 17
	v_readlane_b32 s41, v254, 18
	global_load_dword v26, v25, s[42:43] offset:8
	v_readlane_b32 s44, v254, 21
	v_readlane_b32 s45, v254, 22
	v_readlane_b32 s46, v254, 23
	v_readlane_b32 s47, v254, 24
	v_readlane_b32 s48, v254, 25
	v_readlane_b32 s49, v254, 26
	v_readlane_b32 s50, v254, 27
	v_readlane_b32 s51, v254, 28
.LBB0_28:
	v_lshl_or_b32 v0, v27, 14, v43
	v_lshl_add_u64 v[76:77], v[22:23], 0, v[0:1]
	global_load_dword v75, v[76:77], off sc1 nt
	v_mov_b32_e32 v76, 1.0
	s_and_b64 vcc, exec, s[4:5]
	v_mov_b32_e32 v77, 1.0
	s_cbranch_vccnz .LBB0_30
	v_readlane_b32 s36, v254, 13
	v_readlane_b32 s42, v254, 19
	v_readlane_b32 s43, v254, 20
	v_readlane_b32 s37, v254, 14
	v_readlane_b32 s38, v254, 15
	v_readlane_b32 s39, v254, 16
	v_readlane_b32 s40, v254, 17
	v_readlane_b32 s41, v254, 18
	global_load_dword v77, v25, s[42:43] offset:16
	v_readlane_b32 s44, v254, 21
	v_readlane_b32 s45, v254, 22
	v_readlane_b32 s46, v254, 23
	v_readlane_b32 s47, v254, 24
	v_readlane_b32 s48, v254, 25
	v_readlane_b32 s49, v254, 26
	v_readlane_b32 s50, v254, 27
	v_readlane_b32 s51, v254, 28
.LBB0_30:
	v_lshl_or_b32 v0, v27, 14, v44
	v_lshl_add_u64 v[78:79], v[22:23], 0, v[0:1]
	global_load_dword v78, v[78:79], off sc1 nt
	s_and_b64 vcc, exec, s[4:5]
	s_cbranch_vccnz .LBB0_32
	v_readlane_b32 s36, v254, 13
	v_readlane_b32 s42, v254, 19
	v_readlane_b32 s43, v254, 20
	v_readlane_b32 s37, v254, 14
	v_readlane_b32 s38, v254, 15
	v_readlane_b32 s39, v254, 16
	v_readlane_b32 s40, v254, 17
	v_readlane_b32 s41, v254, 18
	global_load_dword v76, v25, s[42:43] offset:24
	v_readlane_b32 s44, v254, 21
	v_readlane_b32 s45, v254, 22
	v_readlane_b32 s46, v254, 23
	v_readlane_b32 s47, v254, 24
	v_readlane_b32 s48, v254, 25
	v_readlane_b32 s49, v254, 26
	v_readlane_b32 s50, v254, 27
	v_readlane_b32 s51, v254, 28
.LBB0_32:
	v_lshl_or_b32 v0, v27, 14, v45
	v_lshl_add_u64 v[80:81], v[22:23], 0, v[0:1]
	global_load_dword v79, v[80:81], off sc1 nt
	v_mov_b32_e32 v80, 1.0
	s_and_b64 vcc, exec, s[4:5]
	v_mov_b32_e32 v81, 1.0
	s_cbranch_vccnz .LBB0_34
	v_readlane_b32 s36, v254, 13
	v_readlane_b32 s42, v254, 19
	v_readlane_b32 s43, v254, 20
	v_readlane_b32 s37, v254, 14
	v_readlane_b32 s38, v254, 15
	v_readlane_b32 s39, v254, 16
	v_readlane_b32 s40, v254, 17
	v_readlane_b32 s41, v254, 18
	global_load_dword v81, v25, s[42:43] offset:32
	v_readlane_b32 s44, v254, 21
	v_readlane_b32 s45, v254, 22
	v_readlane_b32 s46, v254, 23
	v_readlane_b32 s47, v254, 24
	v_readlane_b32 s48, v254, 25
	v_readlane_b32 s49, v254, 26
	v_readlane_b32 s50, v254, 27
	v_readlane_b32 s51, v254, 28
.LBB0_34:
	v_lshl_or_b32 v0, v27, 14, v46
	v_lshl_add_u64 v[82:83], v[22:23], 0, v[0:1]
	global_load_dword v82, v[82:83], off sc1 nt
	s_and_b64 vcc, exec, s[4:5]
	s_cbranch_vccnz .LBB0_36
	v_readlane_b32 s36, v254, 13
	v_readlane_b32 s42, v254, 19
	v_readlane_b32 s43, v254, 20
	v_readlane_b32 s37, v254, 14
	v_readlane_b32 s38, v254, 15
	v_readlane_b32 s39, v254, 16
	v_readlane_b32 s40, v254, 17
	v_readlane_b32 s41, v254, 18
	global_load_dword v80, v25, s[42:43] offset:40
	v_readlane_b32 s44, v254, 21
	v_readlane_b32 s45, v254, 22
	v_readlane_b32 s46, v254, 23
	v_readlane_b32 s47, v254, 24
	v_readlane_b32 s48, v254, 25
	v_readlane_b32 s49, v254, 26
	v_readlane_b32 s50, v254, 27
	v_readlane_b32 s51, v254, 28
.LBB0_36:
	v_lshl_or_b32 v0, v27, 14, v47
	v_lshl_add_u64 v[84:85], v[22:23], 0, v[0:1]
	global_load_dword v83, v[84:85], off sc1 nt
	v_mov_b32_e32 v84, 1.0
	s_and_b64 vcc, exec, s[4:5]
	v_mov_b32_e32 v85, 1.0
	s_cbranch_vccnz .LBB0_38
	v_readlane_b32 s36, v254, 13
	v_readlane_b32 s42, v254, 19
	v_readlane_b32 s43, v254, 20
	v_readlane_b32 s37, v254, 14
	v_readlane_b32 s38, v254, 15
	v_readlane_b32 s39, v254, 16
	v_readlane_b32 s40, v254, 17
	v_readlane_b32 s41, v254, 18
	global_load_dword v85, v25, s[42:43] offset:48
	v_readlane_b32 s44, v254, 21
	v_readlane_b32 s45, v254, 22
	v_readlane_b32 s46, v254, 23
	v_readlane_b32 s47, v254, 24
	v_readlane_b32 s48, v254, 25
	v_readlane_b32 s49, v254, 26
	v_readlane_b32 s50, v254, 27
	v_readlane_b32 s51, v254, 28
.LBB0_38:
	v_lshl_or_b32 v0, v27, 14, v48
	v_lshl_add_u64 v[86:87], v[22:23], 0, v[0:1]
	global_load_dword v86, v[86:87], off sc1 nt
	s_and_b64 vcc, exec, s[4:5]
	s_cbranch_vccnz .LBB0_40
	v_readlane_b32 s36, v254, 13
	v_readlane_b32 s42, v254, 19
	v_readlane_b32 s43, v254, 20
	v_readlane_b32 s37, v254, 14
	v_readlane_b32 s38, v254, 15
	v_readlane_b32 s39, v254, 16
	v_readlane_b32 s40, v254, 17
	v_readlane_b32 s41, v254, 18
	global_load_dword v84, v25, s[42:43] offset:56
	v_readlane_b32 s44, v254, 21
	v_readlane_b32 s45, v254, 22
	v_readlane_b32 s46, v254, 23
	v_readlane_b32 s47, v254, 24
	v_readlane_b32 s48, v254, 25
	v_readlane_b32 s49, v254, 26
	v_readlane_b32 s50, v254, 27
	v_readlane_b32 s51, v254, 28
.LBB0_40:
	v_lshl_or_b32 v0, v27, 14, v49
	v_lshl_add_u64 v[88:89], v[22:23], 0, v[0:1]
	global_load_dword v87, v[88:89], off sc1 nt
	v_mov_b32_e32 v88, 1.0
	s_and_b64 vcc, exec, s[4:5]
	v_mov_b32_e32 v89, 1.0
	s_cbranch_vccnz .LBB0_42
	v_readlane_b32 s36, v254, 13
	v_readlane_b32 s42, v254, 19
	v_readlane_b32 s43, v254, 20
	v_readlane_b32 s37, v254, 14
	v_readlane_b32 s38, v254, 15
	v_readlane_b32 s39, v254, 16
	v_readlane_b32 s40, v254, 17
	v_readlane_b32 s41, v254, 18
	global_load_dword v89, v25, s[42:43] offset:64
	v_readlane_b32 s44, v254, 21
	v_readlane_b32 s45, v254, 22
	v_readlane_b32 s46, v254, 23
	v_readlane_b32 s47, v254, 24
	v_readlane_b32 s48, v254, 25
	v_readlane_b32 s49, v254, 26
	v_readlane_b32 s50, v254, 27
	v_readlane_b32 s51, v254, 28
.LBB0_42:
	v_lshl_or_b32 v0, v27, 14, v50
	v_lshl_add_u64 v[90:91], v[22:23], 0, v[0:1]
	global_load_dword v90, v[90:91], off sc1 nt
	s_and_b64 vcc, exec, s[4:5]
	s_cbranch_vccnz .LBB0_44
	v_readlane_b32 s36, v254, 13
	v_readlane_b32 s42, v254, 19
	v_readlane_b32 s43, v254, 20
	v_readlane_b32 s37, v254, 14
	v_readlane_b32 s38, v254, 15
	v_readlane_b32 s39, v254, 16
	v_readlane_b32 s40, v254, 17
	v_readlane_b32 s41, v254, 18
	global_load_dword v88, v25, s[42:43] offset:72
	v_readlane_b32 s44, v254, 21
	v_readlane_b32 s45, v254, 22
	v_readlane_b32 s46, v254, 23
	v_readlane_b32 s47, v254, 24
	v_readlane_b32 s48, v254, 25
	v_readlane_b32 s49, v254, 26
	v_readlane_b32 s50, v254, 27
	v_readlane_b32 s51, v254, 28
.LBB0_44:
	v_lshl_or_b32 v0, v27, 14, v51
	v_lshl_add_u64 v[92:93], v[22:23], 0, v[0:1]
	global_load_dword v91, v[92:93], off sc1 nt
	v_mov_b32_e32 v92, 1.0
	s_and_b64 vcc, exec, s[4:5]
	v_mov_b32_e32 v93, 1.0
	s_cbranch_vccnz .LBB0_46
	v_readlane_b32 s36, v254, 13
	v_readlane_b32 s42, v254, 19
	v_readlane_b32 s43, v254, 20
	v_readlane_b32 s37, v254, 14
	v_readlane_b32 s38, v254, 15
	v_readlane_b32 s39, v254, 16
	v_readlane_b32 s40, v254, 17
	v_readlane_b32 s41, v254, 18
	global_load_dword v93, v25, s[42:43] offset:80
	v_readlane_b32 s44, v254, 21
	v_readlane_b32 s45, v254, 22
	v_readlane_b32 s46, v254, 23
	v_readlane_b32 s47, v254, 24
	v_readlane_b32 s48, v254, 25
	v_readlane_b32 s49, v254, 26
	v_readlane_b32 s50, v254, 27
	v_readlane_b32 s51, v254, 28
.LBB0_46:
	v_lshl_or_b32 v0, v27, 14, v52
	v_lshl_add_u64 v[94:95], v[22:23], 0, v[0:1]
	global_load_dword v94, v[94:95], off sc1 nt
	s_and_b64 vcc, exec, s[4:5]
	s_cbranch_vccnz .LBB0_48
	v_readlane_b32 s36, v254, 13
	v_readlane_b32 s42, v254, 19
	v_readlane_b32 s43, v254, 20
	v_readlane_b32 s37, v254, 14
	v_readlane_b32 s38, v254, 15
	v_readlane_b32 s39, v254, 16
	v_readlane_b32 s40, v254, 17
	v_readlane_b32 s41, v254, 18
	global_load_dword v92, v25, s[42:43] offset:88
	v_readlane_b32 s44, v254, 21
	v_readlane_b32 s45, v254, 22
	v_readlane_b32 s46, v254, 23
	v_readlane_b32 s47, v254, 24
	v_readlane_b32 s48, v254, 25
	v_readlane_b32 s49, v254, 26
	v_readlane_b32 s50, v254, 27
	v_readlane_b32 s51, v254, 28
.LBB0_48:
	v_lshl_or_b32 v0, v27, 14, v53
	v_lshl_add_u64 v[96:97], v[22:23], 0, v[0:1]
	global_load_dword v95, v[96:97], off sc1 nt
	v_mov_b32_e32 v96, 1.0
	s_and_b64 vcc, exec, s[4:5]
	v_mov_b32_e32 v97, 1.0
	s_cbranch_vccnz .LBB0_50
	v_readlane_b32 s36, v254, 13
	v_readlane_b32 s42, v254, 19
	v_readlane_b32 s43, v254, 20
	v_readlane_b32 s37, v254, 14
	v_readlane_b32 s38, v254, 15
	v_readlane_b32 s39, v254, 16
	v_readlane_b32 s40, v254, 17
	v_readlane_b32 s41, v254, 18
	global_load_dword v97, v25, s[42:43] offset:96
	v_readlane_b32 s44, v254, 21
	v_readlane_b32 s45, v254, 22
	v_readlane_b32 s46, v254, 23
	v_readlane_b32 s47, v254, 24
	v_readlane_b32 s48, v254, 25
	v_readlane_b32 s49, v254, 26
	v_readlane_b32 s50, v254, 27
	v_readlane_b32 s51, v254, 28
.LBB0_50:
	v_lshl_or_b32 v0, v27, 14, v54
	v_lshl_add_u64 v[98:99], v[22:23], 0, v[0:1]
	global_load_dword v98, v[98:99], off sc1 nt
	s_and_b64 vcc, exec, s[4:5]
	s_cbranch_vccnz .LBB0_52
	v_readlane_b32 s36, v254, 13
	v_readlane_b32 s42, v254, 19
	v_readlane_b32 s43, v254, 20
	v_readlane_b32 s37, v254, 14
	v_readlane_b32 s38, v254, 15
	v_readlane_b32 s39, v254, 16
	v_readlane_b32 s40, v254, 17
	v_readlane_b32 s41, v254, 18
	global_load_dword v96, v25, s[42:43] offset:104
	v_readlane_b32 s44, v254, 21
	v_readlane_b32 s45, v254, 22
	v_readlane_b32 s46, v254, 23
	v_readlane_b32 s47, v254, 24
	v_readlane_b32 s48, v254, 25
	v_readlane_b32 s49, v254, 26
	v_readlane_b32 s50, v254, 27
	v_readlane_b32 s51, v254, 28
.LBB0_52:
	v_lshl_or_b32 v0, v27, 14, v55
	v_lshl_add_u64 v[100:101], v[22:23], 0, v[0:1]
	global_load_dword v99, v[100:101], off sc1 nt
	v_mov_b32_e32 v100, 1.0
	s_and_b64 vcc, exec, s[4:5]
	v_mov_b32_e32 v101, 1.0
	s_cbranch_vccnz .LBB0_54
	v_readlane_b32 s36, v254, 13
	v_readlane_b32 s42, v254, 19
	v_readlane_b32 s43, v254, 20
	v_readlane_b32 s37, v254, 14
	v_readlane_b32 s38, v254, 15
	v_readlane_b32 s39, v254, 16
	v_readlane_b32 s40, v254, 17
	v_readlane_b32 s41, v254, 18
	global_load_dword v101, v25, s[42:43] offset:112
	v_readlane_b32 s44, v254, 21
	v_readlane_b32 s45, v254, 22
	v_readlane_b32 s46, v254, 23
	v_readlane_b32 s47, v254, 24
	v_readlane_b32 s48, v254, 25
	v_readlane_b32 s49, v254, 26
	v_readlane_b32 s50, v254, 27
	v_readlane_b32 s51, v254, 28
.LBB0_54:
	v_lshl_or_b32 v0, v27, 14, v56
	v_lshl_add_u64 v[102:103], v[22:23], 0, v[0:1]
	global_load_dword v102, v[102:103], off sc1 nt
	s_and_b64 vcc, exec, s[4:5]
	s_cbranch_vccnz .LBB0_56
	v_readlane_b32 s36, v254, 13
	v_readlane_b32 s42, v254, 19
	v_readlane_b32 s43, v254, 20
	v_readlane_b32 s37, v254, 14
	v_readlane_b32 s38, v254, 15
	v_readlane_b32 s39, v254, 16
	v_readlane_b32 s40, v254, 17
	v_readlane_b32 s41, v254, 18
	global_load_dword v100, v25, s[42:43] offset:120
	v_readlane_b32 s44, v254, 21
	v_readlane_b32 s45, v254, 22
	v_readlane_b32 s46, v254, 23
	v_readlane_b32 s47, v254, 24
	v_readlane_b32 s48, v254, 25
	v_readlane_b32 s49, v254, 26
	v_readlane_b32 s50, v254, 27
	v_readlane_b32 s51, v254, 28
.LBB0_56:
	v_lshl_or_b32 v0, v27, 14, v57
	v_lshl_add_u64 v[104:105], v[22:23], 0, v[0:1]
	global_load_dword v103, v[104:105], off sc1 nt
	v_mov_b32_e32 v104, 1.0
	s_and_b64 vcc, exec, s[4:5]
	v_mov_b32_e32 v105, 1.0
	s_cbranch_vccnz .LBB0_58
	v_readlane_b32 s36, v254, 13
	v_readlane_b32 s42, v254, 19
	v_readlane_b32 s43, v254, 20
	v_readlane_b32 s37, v254, 14
	v_readlane_b32 s38, v254, 15
	v_readlane_b32 s39, v254, 16
	v_readlane_b32 s40, v254, 17
	v_readlane_b32 s41, v254, 18
	global_load_dword v105, v25, s[42:43] offset:128
	v_readlane_b32 s44, v254, 21
	v_readlane_b32 s45, v254, 22
	v_readlane_b32 s46, v254, 23
	v_readlane_b32 s47, v254, 24
	v_readlane_b32 s48, v254, 25
	v_readlane_b32 s49, v254, 26
	v_readlane_b32 s50, v254, 27
	v_readlane_b32 s51, v254, 28
.LBB0_58:
	v_lshl_or_b32 v0, v27, 14, v58
	v_lshl_add_u64 v[106:107], v[22:23], 0, v[0:1]
	global_load_dword v106, v[106:107], off sc1 nt
	s_and_b64 vcc, exec, s[4:5]
	s_cbranch_vccnz .LBB0_60
	v_readlane_b32 s36, v254, 13
	v_readlane_b32 s42, v254, 19
	v_readlane_b32 s43, v254, 20
	v_readlane_b32 s37, v254, 14
	v_readlane_b32 s38, v254, 15
	v_readlane_b32 s39, v254, 16
	v_readlane_b32 s40, v254, 17
	v_readlane_b32 s41, v254, 18
	global_load_dword v104, v25, s[42:43] offset:136
	v_readlane_b32 s44, v254, 21
	v_readlane_b32 s45, v254, 22
	v_readlane_b32 s46, v254, 23
	v_readlane_b32 s47, v254, 24
	v_readlane_b32 s48, v254, 25
	v_readlane_b32 s49, v254, 26
	v_readlane_b32 s50, v254, 27
	v_readlane_b32 s51, v254, 28
.LBB0_60:
	v_lshl_or_b32 v0, v27, 14, v59
	v_lshl_add_u64 v[108:109], v[22:23], 0, v[0:1]
	global_load_dword v107, v[108:109], off sc1 nt
	v_mov_b32_e32 v108, 1.0
	s_and_b64 vcc, exec, s[4:5]
	v_mov_b32_e32 v109, 1.0
	s_cbranch_vccnz .LBB0_62
	v_readlane_b32 s36, v254, 13
	v_readlane_b32 s42, v254, 19
	v_readlane_b32 s43, v254, 20
	v_readlane_b32 s37, v254, 14
	v_readlane_b32 s38, v254, 15
	v_readlane_b32 s39, v254, 16
	v_readlane_b32 s40, v254, 17
	v_readlane_b32 s41, v254, 18
	global_load_dword v109, v25, s[42:43] offset:144
	v_readlane_b32 s44, v254, 21
	v_readlane_b32 s45, v254, 22
	v_readlane_b32 s46, v254, 23
	v_readlane_b32 s47, v254, 24
	v_readlane_b32 s48, v254, 25
	v_readlane_b32 s49, v254, 26
	v_readlane_b32 s50, v254, 27
	v_readlane_b32 s51, v254, 28
.LBB0_62:
	v_lshl_or_b32 v0, v27, 14, v60
	v_lshl_add_u64 v[110:111], v[22:23], 0, v[0:1]
	global_load_dword v110, v[110:111], off sc1 nt
	s_and_b64 vcc, exec, s[4:5]
	s_cbranch_vccnz .LBB0_64
	v_readlane_b32 s36, v254, 13
	v_readlane_b32 s42, v254, 19
	v_readlane_b32 s43, v254, 20
	v_readlane_b32 s37, v254, 14
	v_readlane_b32 s38, v254, 15
	v_readlane_b32 s39, v254, 16
	v_readlane_b32 s40, v254, 17
	v_readlane_b32 s41, v254, 18
	global_load_dword v108, v25, s[42:43] offset:152
	v_readlane_b32 s44, v254, 21
	v_readlane_b32 s45, v254, 22
	v_readlane_b32 s46, v254, 23
	v_readlane_b32 s47, v254, 24
	v_readlane_b32 s48, v254, 25
	v_readlane_b32 s49, v254, 26
	v_readlane_b32 s50, v254, 27
	v_readlane_b32 s51, v254, 28
.LBB0_64:
	v_lshl_or_b32 v0, v27, 14, v61
	v_lshl_add_u64 v[112:113], v[22:23], 0, v[0:1]
	global_load_dword v111, v[112:113], off sc1 nt
	v_mov_b32_e32 v112, 1.0
	s_and_b64 vcc, exec, s[4:5]
	v_mov_b32_e32 v113, 1.0
	s_cbranch_vccnz .LBB0_66
	v_readlane_b32 s36, v254, 13
	v_readlane_b32 s42, v254, 19
	v_readlane_b32 s43, v254, 20
	v_readlane_b32 s37, v254, 14
	v_readlane_b32 s38, v254, 15
	v_readlane_b32 s39, v254, 16
	v_readlane_b32 s40, v254, 17
	v_readlane_b32 s41, v254, 18
	global_load_dword v113, v25, s[42:43] offset:160
	v_readlane_b32 s44, v254, 21
	v_readlane_b32 s45, v254, 22
	v_readlane_b32 s46, v254, 23
	v_readlane_b32 s47, v254, 24
	v_readlane_b32 s48, v254, 25
	v_readlane_b32 s49, v254, 26
	v_readlane_b32 s50, v254, 27
	v_readlane_b32 s51, v254, 28
.LBB0_66:
	v_lshl_or_b32 v0, v27, 14, v62
	v_lshl_add_u64 v[114:115], v[22:23], 0, v[0:1]
	global_load_dword v114, v[114:115], off sc1 nt
	s_and_b64 vcc, exec, s[4:5]
	s_cbranch_vccnz .LBB0_68
	v_readlane_b32 s36, v254, 13
	v_readlane_b32 s42, v254, 19
	v_readlane_b32 s43, v254, 20
	v_readlane_b32 s37, v254, 14
	v_readlane_b32 s38, v254, 15
	v_readlane_b32 s39, v254, 16
	v_readlane_b32 s40, v254, 17
	v_readlane_b32 s41, v254, 18
	global_load_dword v112, v25, s[42:43] offset:168
	v_readlane_b32 s44, v254, 21
	v_readlane_b32 s45, v254, 22
	v_readlane_b32 s46, v254, 23
	v_readlane_b32 s47, v254, 24
	v_readlane_b32 s48, v254, 25
	v_readlane_b32 s49, v254, 26
	v_readlane_b32 s50, v254, 27
	v_readlane_b32 s51, v254, 28
.LBB0_68:
	v_lshl_or_b32 v0, v27, 14, v63
	v_lshl_add_u64 v[116:117], v[22:23], 0, v[0:1]
	global_load_dword v115, v[116:117], off sc1 nt
	v_mov_b32_e32 v116, 1.0
	s_and_b64 vcc, exec, s[4:5]
	v_mov_b32_e32 v117, 1.0
	s_cbranch_vccnz .LBB0_70
	v_readlane_b32 s36, v254, 13
	v_readlane_b32 s42, v254, 19
	v_readlane_b32 s43, v254, 20
	v_readlane_b32 s37, v254, 14
	v_readlane_b32 s38, v254, 15
	v_readlane_b32 s39, v254, 16
	v_readlane_b32 s40, v254, 17
	v_readlane_b32 s41, v254, 18
	global_load_dword v117, v25, s[42:43] offset:176
	v_readlane_b32 s44, v254, 21
	v_readlane_b32 s45, v254, 22
	v_readlane_b32 s46, v254, 23
	v_readlane_b32 s47, v254, 24
	v_readlane_b32 s48, v254, 25
	v_readlane_b32 s49, v254, 26
	v_readlane_b32 s50, v254, 27
	v_readlane_b32 s51, v254, 28
.LBB0_70:
	v_lshl_or_b32 v0, v27, 14, v64
	v_lshl_add_u64 v[118:119], v[22:23], 0, v[0:1]
	global_load_dword v118, v[118:119], off sc1 nt
	s_and_b64 vcc, exec, s[4:5]
	s_cbranch_vccnz .LBB0_72
	v_readlane_b32 s36, v254, 13
	v_readlane_b32 s42, v254, 19
	v_readlane_b32 s43, v254, 20
	v_readlane_b32 s37, v254, 14
	v_readlane_b32 s38, v254, 15
	v_readlane_b32 s39, v254, 16
	v_readlane_b32 s40, v254, 17
	v_readlane_b32 s41, v254, 18
	global_load_dword v116, v25, s[42:43] offset:184
	v_readlane_b32 s44, v254, 21
	v_readlane_b32 s45, v254, 22
	v_readlane_b32 s46, v254, 23
	v_readlane_b32 s47, v254, 24
	v_readlane_b32 s48, v254, 25
	v_readlane_b32 s49, v254, 26
	v_readlane_b32 s50, v254, 27
	v_readlane_b32 s51, v254, 28
.LBB0_72:
	v_lshl_or_b32 v0, v27, 14, v65
	v_lshl_add_u64 v[120:121], v[22:23], 0, v[0:1]
	global_load_dword v119, v[120:121], off sc1 nt
	v_mov_b32_e32 v120, 1.0
	s_and_b64 vcc, exec, s[4:5]
	v_mov_b32_e32 v121, 1.0
	s_cbranch_vccnz .LBB0_74
	v_readlane_b32 s36, v254, 13
	v_readlane_b32 s42, v254, 19
	v_readlane_b32 s43, v254, 20
	v_readlane_b32 s37, v254, 14
	v_readlane_b32 s38, v254, 15
	v_readlane_b32 s39, v254, 16
	v_readlane_b32 s40, v254, 17
	v_readlane_b32 s41, v254, 18
	global_load_dword v121, v25, s[42:43] offset:192
	v_readlane_b32 s44, v254, 21
	v_readlane_b32 s45, v254, 22
	v_readlane_b32 s46, v254, 23
	v_readlane_b32 s47, v254, 24
	v_readlane_b32 s48, v254, 25
	v_readlane_b32 s49, v254, 26
	v_readlane_b32 s50, v254, 27
	v_readlane_b32 s51, v254, 28
.LBB0_74:
	v_lshl_or_b32 v0, v27, 14, v66
	v_lshl_add_u64 v[122:123], v[22:23], 0, v[0:1]
	global_load_dword v122, v[122:123], off sc1 nt
	s_and_b64 vcc, exec, s[4:5]
	s_cbranch_vccnz .LBB0_76
	v_readlane_b32 s36, v254, 13
	v_readlane_b32 s42, v254, 19
	v_readlane_b32 s43, v254, 20
	v_readlane_b32 s37, v254, 14
	v_readlane_b32 s38, v254, 15
	v_readlane_b32 s39, v254, 16
	v_readlane_b32 s40, v254, 17
	v_readlane_b32 s41, v254, 18
	global_load_dword v120, v25, s[42:43] offset:200
	v_readlane_b32 s44, v254, 21
	v_readlane_b32 s45, v254, 22
	v_readlane_b32 s46, v254, 23
	v_readlane_b32 s47, v254, 24
	v_readlane_b32 s48, v254, 25
	v_readlane_b32 s49, v254, 26
	v_readlane_b32 s50, v254, 27
	v_readlane_b32 s51, v254, 28
.LBB0_76:
	v_lshl_or_b32 v0, v27, 14, v67
	v_lshl_add_u64 v[124:125], v[22:23], 0, v[0:1]
	global_load_dword v123, v[124:125], off sc1 nt
	v_mov_b32_e32 v124, 1.0
	s_and_b64 vcc, exec, s[4:5]
	v_mov_b32_e32 v125, 1.0
	s_cbranch_vccnz .LBB0_78
	v_readlane_b32 s36, v254, 13
	v_readlane_b32 s42, v254, 19
	v_readlane_b32 s43, v254, 20
	v_readlane_b32 s37, v254, 14
	v_readlane_b32 s38, v254, 15
	v_readlane_b32 s39, v254, 16
	v_readlane_b32 s40, v254, 17
	v_readlane_b32 s41, v254, 18
	global_load_dword v125, v25, s[42:43] offset:208
	v_readlane_b32 s44, v254, 21
	v_readlane_b32 s45, v254, 22
	v_readlane_b32 s46, v254, 23
	v_readlane_b32 s47, v254, 24
	v_readlane_b32 s48, v254, 25
	v_readlane_b32 s49, v254, 26
	v_readlane_b32 s50, v254, 27
	v_readlane_b32 s51, v254, 28
.LBB0_78:
	v_lshl_or_b32 v0, v27, 14, v68
	v_lshl_add_u64 v[126:127], v[22:23], 0, v[0:1]
	global_load_dword v126, v[126:127], off sc1 nt
	s_and_b64 vcc, exec, s[4:5]
	s_cbranch_vccnz .LBB0_80
	v_readlane_b32 s36, v254, 13
	v_readlane_b32 s42, v254, 19
	v_readlane_b32 s43, v254, 20
	v_readlane_b32 s37, v254, 14
	v_readlane_b32 s38, v254, 15
	v_readlane_b32 s39, v254, 16
	v_readlane_b32 s40, v254, 17
	v_readlane_b32 s41, v254, 18
	global_load_dword v124, v25, s[42:43] offset:216
	v_readlane_b32 s44, v254, 21
	v_readlane_b32 s45, v254, 22
	v_readlane_b32 s46, v254, 23
	v_readlane_b32 s47, v254, 24
	v_readlane_b32 s48, v254, 25
	v_readlane_b32 s49, v254, 26
	v_readlane_b32 s50, v254, 27
	v_readlane_b32 s51, v254, 28
.LBB0_80:
	v_lshl_or_b32 v0, v27, 14, v69
	v_lshl_add_u64 v[128:129], v[22:23], 0, v[0:1]
	global_load_dword v127, v[128:129], off sc1 nt
	v_mov_b32_e32 v128, 1.0
	s_and_b64 vcc, exec, s[4:5]
	v_mov_b32_e32 v129, 1.0
	s_cbranch_vccnz .LBB0_82
	v_readlane_b32 s36, v254, 13
	v_readlane_b32 s42, v254, 19
	v_readlane_b32 s43, v254, 20
	v_readlane_b32 s37, v254, 14
	v_readlane_b32 s38, v254, 15
	v_readlane_b32 s39, v254, 16
	v_readlane_b32 s40, v254, 17
	v_readlane_b32 s41, v254, 18
	global_load_dword v129, v25, s[42:43] offset:224
	v_readlane_b32 s44, v254, 21
	v_readlane_b32 s45, v254, 22
	v_readlane_b32 s46, v254, 23
	v_readlane_b32 s47, v254, 24
	v_readlane_b32 s48, v254, 25
	v_readlane_b32 s49, v254, 26
	v_readlane_b32 s50, v254, 27
	v_readlane_b32 s51, v254, 28
.LBB0_82:
	v_lshl_or_b32 v0, v27, 14, v70
	v_lshl_add_u64 v[130:131], v[22:23], 0, v[0:1]
	global_load_dword v130, v[130:131], off sc1 nt
	s_and_b64 vcc, exec, s[4:5]
	s_cbranch_vccnz .LBB0_84
	v_readlane_b32 s36, v254, 13
	v_readlane_b32 s42, v254, 19
	v_readlane_b32 s43, v254, 20
	v_readlane_b32 s37, v254, 14
	v_readlane_b32 s38, v254, 15
	v_readlane_b32 s39, v254, 16
	v_readlane_b32 s40, v254, 17
	v_readlane_b32 s41, v254, 18
	global_load_dword v128, v25, s[42:43] offset:232
	v_readlane_b32 s44, v254, 21
	v_readlane_b32 s45, v254, 22
	v_readlane_b32 s46, v254, 23
	v_readlane_b32 s47, v254, 24
	v_readlane_b32 s48, v254, 25
	v_readlane_b32 s49, v254, 26
	v_readlane_b32 s50, v254, 27
	v_readlane_b32 s51, v254, 28
.LBB0_84:
	v_lshl_or_b32 v0, v27, 14, v71
	v_lshl_add_u64 v[132:133], v[22:23], 0, v[0:1]
	global_load_dword v131, v[132:133], off sc1 nt
	v_mov_b32_e32 v132, 1.0
	s_and_b64 vcc, exec, s[4:5]
	v_mov_b32_e32 v133, 1.0
	s_cbranch_vccnz .LBB0_86
	v_readlane_b32 s36, v254, 13
	v_readlane_b32 s42, v254, 19
	v_readlane_b32 s43, v254, 20
	v_readlane_b32 s37, v254, 14
	v_readlane_b32 s38, v254, 15
	v_readlane_b32 s39, v254, 16
	v_readlane_b32 s40, v254, 17
	v_readlane_b32 s41, v254, 18
	global_load_dword v133, v25, s[42:43] offset:240
	v_readlane_b32 s44, v254, 21
	v_readlane_b32 s45, v254, 22
	v_readlane_b32 s46, v254, 23
	v_readlane_b32 s47, v254, 24
	v_readlane_b32 s48, v254, 25
	v_readlane_b32 s49, v254, 26
	v_readlane_b32 s50, v254, 27
	v_readlane_b32 s51, v254, 28
.LBB0_86:
	v_lshl_or_b32 v0, v27, 14, v72
	v_lshl_add_u64 v[22:23], v[22:23], 0, v[0:1]
	global_load_dword v0, v[22:23], off sc1 nt
	s_and_b64 vcc, exec, s[4:5]
	s_cbranch_vccnz .LBB0_88
	v_readlane_b32 s36, v254, 13
	v_readlane_b32 s42, v254, 19
	v_readlane_b32 s43, v254, 20
	v_readlane_b32 s37, v254, 14
	v_readlane_b32 s38, v254, 15
	v_readlane_b32 s39, v254, 16
	v_readlane_b32 s40, v254, 17
	v_readlane_b32 s41, v254, 18
	global_load_dword v132, v25, s[42:43] offset:248
	v_readlane_b32 s44, v254, 21
	v_readlane_b32 s45, v254, 22
	v_readlane_b32 s46, v254, 23
	v_readlane_b32 s47, v254, 24
	v_readlane_b32 s48, v254, 25
	v_readlane_b32 s49, v254, 26
	v_readlane_b32 s50, v254, 27
	v_readlane_b32 s51, v254, 28

.LBB0_90:
	s_andn2_b64 vcc, exec, s[2:3]
	s_cbranch_vccnz .LBB0_92
	s_add_i32 s0, s25, 0x1400
	s_and_b32 s3, s0, 0x1ffc0
	s_and_b32 s2, s9, 0x3e0
	v_or_b32_e32 v0, s3, v28
	s_lshl_b32 s0, s2, 2
	v_lshl_add_u64 v[22:23], v[18:19], 0, s[0:1]
	v_lshlrev_b32_e32 v0, 12, v0
	v_lshl_add_u64 v[22:23], v[22:23], 0, v[0:1]
	v_add_co_u32_e32 v24, vcc, 0x2000, v22
	s_lshl_b32 s0, s3, 1
	s_nop 0
	v_addc_co_u32_e32 v25, vcc, 0, v23, vcc
	v_add_co_u32_e32 v26, vcc, 0x4000, v22
	s_nop 1
	v_addc_co_u32_e32 v27, vcc, 0, v23, vcc
	v_add_co_u32_e32 v74, vcc, 0x6000, v22
	s_nop 1
	v_addc_co_u32_e32 v75, vcc, 0, v23, vcc
	v_add_co_u32_e32 v76, vcc, 0x8000, v22
	s_nop 1
	v_addc_co_u32_e32 v77, vcc, 0, v23, vcc
	v_add_co_u32_e32 v78, vcc, 0xa000, v22
	s_nop 1
	v_addc_co_u32_e32 v79, vcc, 0, v23, vcc
	v_add_co_u32_e32 v80, vcc, 0xc000, v22
	s_nop 1
	v_addc_co_u32_e32 v81, vcc, 0, v23, vcc
	v_add_co_u32_e32 v82, vcc, 0xe000, v22
	s_nop 1
	v_addc_co_u32_e32 v83, vcc, 0, v23, vcc
	global_load_dword v0, v[22:23], off sc1 nt
	global_load_dword v73, v[24:25], off sc1 nt
	global_load_dword v86, v[26:27], off sc1 nt
	global_load_dword v87, v[74:75], off sc1 nt
	global_load_dword v88, v[76:77], off sc1 nt
	global_load_dword v89, v[78:79], off sc1 nt
	global_load_dword v90, v[80:81], off sc1 nt
	global_load_dword v91, v[82:83], off sc1 nt
	v_add_co_u32_e32 v24, vcc, 0x10000, v22
	s_nop 1
	v_addc_co_u32_e32 v25, vcc, 0, v23, vcc
	v_add_co_u32_e32 v26, vcc, 0x12000, v22
	s_nop 1
	v_addc_co_u32_e32 v27, vcc, 0, v23, vcc
	v_add_co_u32_e32 v74, vcc, 0x14000, v22
	s_nop 1
	v_addc_co_u32_e32 v75, vcc, 0, v23, vcc
	v_add_co_u32_e32 v76, vcc, 0x16000, v22
	s_nop 1
	v_addc_co_u32_e32 v77, vcc, 0, v23, vcc
	v_add_co_u32_e32 v78, vcc, 0x18000, v22
	s_nop 1
	v_addc_co_u32_e32 v79, vcc, 0, v23, vcc
	v_add_co_u32_e32 v80, vcc, 0x1a000, v22
	s_nop 1
	v_addc_co_u32_e32 v81, vcc, 0, v23, vcc
	v_add_co_u32_e32 v82, vcc, 0x1c000, v22
	s_nop 1
	v_addc_co_u32_e32 v83, vcc, 0, v23, vcc
	v_add_co_u32_e32 v84, vcc, s24, v22
	s_nop 1
	v_addc_co_u32_e32 v85, vcc, 0, v23, vcc
	global_load_dword v92, v[24:25], off sc1 nt
	global_load_dword v93, v[26:27], off sc1 nt
	global_load_dword v94, v[74:75], off sc1 nt
	global_load_dword v95, v[76:77], off sc1 nt
	global_load_dword v96, v[78:79], off sc1 nt
	global_load_dword v97, v[80:81], off sc1 nt
	global_load_dword v98, v[82:83], off sc1 nt
	global_load_dword v99, v[84:85], off sc1 nt
	v_add_co_u32_e32 v24, vcc, 0x20000, v22
	s_nop 1
	v_addc_co_u32_e32 v25, vcc, 0, v23, vcc
	v_add_co_u32_e32 v26, vcc, 0x22000, v22
	s_nop 1
	v_addc_co_u32_e32 v27, vcc, 0, v23, vcc
	v_add_co_u32_e32 v74, vcc, 0x24000, v22
	s_nop 1
	v_addc_co_u32_e32 v75, vcc, 0, v23, vcc
	v_add_co_u32_e32 v76, vcc, 0x26000, v22
	s_nop 1
	v_addc_co_u32_e32 v77, vcc, 0, v23, vcc
	v_add_co_u32_e32 v78, vcc, 0x28000, v22
	s_nop 1
	v_addc_co_u32_e32 v79, vcc, 0, v23, vcc
	v_add_co_u32_e32 v80, vcc, 0x2a000, v22
	s_nop 1
	v_addc_co_u32_e32 v81, vcc, 0, v23, vcc
	v_add_co_u32_e32 v82, vcc, 0x2c000, v22
	s_nop 1
	v_addc_co_u32_e32 v83, vcc, 0, v23, vcc
	v_add_co_u32_e32 v84, vcc, 0x2e000, v22
	s_nop 1
	v_addc_co_u32_e32 v85, vcc, 0, v23, vcc
	global_load_dword v100, v[24:25], off sc1 nt
	global_load_dword v101, v[26:27], off sc1 nt
	global_load_dword v102, v[74:75], off sc1 nt
	global_load_dword v103, v[76:77], off sc1 nt
	global_load_dword v104, v[78:79], off sc1 nt
	global_load_dword v105, v[80:81], off sc1 nt
	global_load_dword v106, v[82:83], off sc1 nt
	s_nop 0
	global_load_dword v84, v[84:85], off sc1 nt
	v_add_co_u32_e32 v24, vcc, 0x30000, v22
	s_nop 1
	v_addc_co_u32_e32 v25, vcc, 0, v23, vcc
	v_add_co_u32_e32 v26, vcc, 0x32000, v22
	s_nop 1
	v_addc_co_u32_e32 v27, vcc, 0, v23, vcc
	v_add_co_u32_e32 v74, vcc, 0x34000, v22
	s_nop 1
	v_addc_co_u32_e32 v75, vcc, 0, v23, vcc
	v_add_co_u32_e32 v76, vcc, 0x36000, v22
	s_nop 1
	v_addc_co_u32_e32 v77, vcc, 0, v23, vcc
	v_add_co_u32_e32 v78, vcc, 0x38000, v22
	s_nop 1
	v_addc_co_u32_e32 v79, vcc, 0, v23, vcc
	v_add_co_u32_e32 v80, vcc, 0x3a000, v22
	s_nop 1
	v_addc_co_u32_e32 v81, vcc, 0, v23, vcc
	v_add_co_u32_e32 v82, vcc, 0x3c000, v22
	s_nop 1
	v_addc_co_u32_e32 v83, vcc, 0, v23, vcc
	v_add_co_u32_e32 v22, vcc, 0x3e000, v22
	s_nop 1
	v_addc_co_u32_e32 v23, vcc, 0, v23, vcc
	global_load_dword v24, v[24:25], off sc1 nt
	s_nop 0
	global_load_dword v25, v[26:27], off sc1 nt
	s_nop 0
	global_load_dword v26, v[74:75], off sc1 nt
	global_load_dword v27, v[76:77], off sc1 nt
	s_nop 0
	global_load_dword v74, v[78:79], off sc1 nt
	global_load_dword v75, v[80:81], off sc1 nt
	global_load_dword v76, v[82:83], off sc1 nt
	s_nop 0
	global_load_dword v22, v[22:23], off sc1 nt
	s_waitcnt vmcnt(30)
	ds_write2_b32 v29, v0, v73 offset1:66
	s_waitcnt vmcnt(28)
	ds_write2_b32 v29, v86, v87 offset0:132 offset1:198
	s_waitcnt vmcnt(26)
	ds_write2_b32 v35, v88, v89 offset0:8 offset1:74
	s_waitcnt vmcnt(24)
	ds_write2_b32 v35, v90, v91 offset0:140 offset1:206
	s_waitcnt vmcnt(22)
	ds_write2_b32 v36, v92, v93 offset0:16 offset1:82
	s_waitcnt vmcnt(20)
	ds_write2_b32 v36, v94, v95 offset0:148 offset1:214
	s_waitcnt vmcnt(18)
	ds_write2_b32 v37, v96, v97 offset0:24 offset1:90
	s_waitcnt vmcnt(16)
	ds_write2_b32 v37, v98, v99 offset0:156 offset1:222
	s_waitcnt vmcnt(14)
	ds_write2_b32 v38, v100, v101 offset0:32 offset1:98
	s_waitcnt vmcnt(12)
	ds_write2_b32 v38, v102, v103 offset0:164 offset1:230
	s_waitcnt vmcnt(10)
	ds_write2_b32 v39, v104, v105 offset0:40 offset1:106
	s_waitcnt vmcnt(8)
	ds_write2_b32 v39, v106, v84 offset0:172 offset1:238
	s_waitcnt vmcnt(6)
	ds_write2_b32 v40, v24, v25 offset0:48 offset1:114
	s_waitcnt vmcnt(4)
	ds_write2_b32 v40, v26, v27 offset0:180 offset1:246
	s_waitcnt vmcnt(2)
	ds_write2_b32 v41, v74, v75 offset0:56 offset1:122
	s_waitcnt vmcnt(0)
	ds_write2_b32 v41, v76, v22 offset0:188 offset1:254
	s_waitcnt lgkmcnt(0)
	ds_read2_b32 v[26:27], v31 offset0:33 offset1:41
	ds_read2_b32 v[74:75], v31 offset1:8
	ds_read2_b32 v[76:77], v31 offset0:66 offset1:74
	ds_read2_b32 v[78:79], v31 offset0:99 offset1:107
	ds_read2_b32 v[80:81], v31 offset0:132 offset1:140
	ds_read2_b32 v[82:83], v31 offset0:165 offset1:173
	ds_read2_b32 v[84:85], v31 offset0:198 offset1:206
	ds_read2_b32 v[86:87], v31 offset0:231 offset1:239
	v_or_b32_e32 v0, s2, v30
	v_lshl_add_u64 v[88:89], v[8:9], 0, s[0:1]
	v_lshlrev_b32_e32 v0, 11, v0
	s_waitcnt lgkmcnt(6)
	v_cvt_pk_bf16_f32 v22, v74, v26
	s_waitcnt lgkmcnt(4)
	v_cvt_pk_bf16_f32 v23, v76, v78
	s_waitcnt lgkmcnt(2)
	v_cvt_pk_bf16_f32 v24, v80, v82
	s_waitcnt lgkmcnt(0)
	v_cvt_pk_bf16_f32 v25, v84, v86
	v_lshl_add_u64 v[90:91], v[88:89], 0, v[0:1]
	global_store_dwordx4 v[90:91], v[22:25], off
	v_or_b32_e32 v0, s2, v32
	v_lshlrev_b32_e32 v0, 11, v0
	v_cvt_pk_bf16_f32 v22, v75, v27
	v_cvt_pk_bf16_f32 v23, v77, v79
	v_cvt_pk_bf16_f32 v24, v81, v83
	v_cvt_pk_bf16_f32 v25, v85, v87
	ds_read2_b32 v[74:75], v31 offset0:49 offset1:57
	ds_read2_b32 v[76:77], v31 offset0:16 offset1:24
	ds_read2_b32 v[78:79], v31 offset0:82 offset1:90
	ds_read2_b32 v[80:81], v31 offset0:115 offset1:123
	ds_read2_b32 v[82:83], v31 offset0:148 offset1:156
	ds_read2_b32 v[84:85], v31 offset0:181 offset1:189
	ds_read2_b32 v[86:87], v31 offset0:214 offset1:222
	ds_read2_b32 v[90:91], v31 offset0:247 offset1:255
	v_lshl_add_u64 v[26:27], v[88:89], 0, v[0:1]
	v_or_b32_e32 v0, s2, v33
	v_lshlrev_b32_e32 v0, 11, v0
	global_store_dwordx4 v[26:27], v[22:25], off
	v_lshl_add_u64 v[26:27], v[88:89], 0, v[0:1]
	v_or_b32_e32 v0, s2, v34
	s_waitcnt lgkmcnt(6)
	v_cvt_pk_bf16_f32 v22, v76, v74
	s_waitcnt lgkmcnt(4)
	v_cvt_pk_bf16_f32 v23, v78, v80
	s_waitcnt lgkmcnt(2)
	v_cvt_pk_bf16_f32 v24, v82, v84
	s_waitcnt lgkmcnt(0)
	v_cvt_pk_bf16_f32 v25, v86, v90
	v_lshlrev_b32_e32 v0, 11, v0
	global_store_dwordx4 v[26:27], v[22:25], off
	v_lshl_add_u64 v[26:27], v[88:89], 0, v[0:1]
	s_nop 0
	v_cvt_pk_bf16_f32 v22, v77, v75
	v_cvt_pk_bf16_f32 v23, v79, v81
	v_cvt_pk_bf16_f32 v24, v83, v85
	v_cvt_pk_bf16_f32 v25, v87, v91
	global_store_dwordx4 v[26:27], v[22:25], off
	s_waitcnt lgkmcnt(0)

.LBB0_93:
	s_andn2_b64 vcc, exec, s[2:3]
	s_cbranch_vccnz .LBB0_14
	s_mul_hi_i32 s0, s29, 0x2aaaaaab
	s_lshr_b32 s2, s0, 31
	s_ashr_i32 s0, s0, 4
	s_add_i32 s0, s0, s2
	s_lshl_b32 s2, s0, 6
	s_mulk_i32 s0, 0xf400
	s_add_i32 s18, s9, s0
	s_ashr_i32 s19, s18, 31
	v_or_b32_e32 v22, s2, v28
	v_lshl_add_u64 v[24:25], s[18:19], 2, v[20:21]
	v_mad_i64_i32 v[26:27], s[4:5], v22, s28, v[24:25]
	global_load_dword v0, v[26:27], off sc1 nt
	v_readlane_b32 s36, v254, 13
	v_ashrrev_i32_e32 v23, 31, v22
	v_cndmask_b32_e64 v26, 0, 1, s[16:17]
	v_readlane_b32 s40, v254, 17
	v_readlane_b32 s41, v254, 18
	v_mov_b32_e32 v73, 1.0
	v_cmp_ne_u32_e64 s[4:5], 1, v26
	s_andn2_b64 vcc, exec, s[16:17]
	v_lshl_add_u64 v[26:27], v[22:23], 2, s[40:41]
	v_mov_b32_e32 v23, 1.0
	v_readlane_b32 s37, v254, 14
	v_readlane_b32 s38, v254, 15
	v_readlane_b32 s39, v254, 16
	v_readlane_b32 s42, v254, 19
	v_readlane_b32 s43, v254, 20
	v_readlane_b32 s44, v254, 21
	v_readlane_b32 s45, v254, 22
	v_readlane_b32 s46, v254, 23
	v_readlane_b32 s47, v254, 24
	v_readlane_b32 s48, v254, 25
	v_readlane_b32 s49, v254, 26
	v_readlane_b32 s50, v254, 27
	v_readlane_b32 s51, v254, 28
	s_cbranch_vccnz .LBB0_96
	global_load_dword v23, v[26:27], off sc1 nt
.LBB0_96:
	v_or_b32_e32 v74, 2, v22
	v_mad_i64_i32 v[74:75], s[30:31], v74, s28, v[24:25]
	global_load_dword v74, v[74:75], off sc1 nt
	s_and_b64 vcc, exec, s[4:5]
	s_cbranch_vccnz .LBB0_98
	global_load_dword v73, v[26:27], off offset:8 sc1 nt
.LBB0_98:
	v_or_b32_e32 v75, 4, v22
	v_mad_i64_i32 v[76:77], s[30:31], v75, s28, v[24:25]
	global_load_dword v75, v[76:77], off sc1 nt
	v_mov_b32_e32 v76, 1.0
	s_and_b64 vcc, exec, s[4:5]
	v_mov_b32_e32 v77, 1.0
	s_cbranch_vccnz .LBB0_100
	global_load_dword v77, v[26:27], off offset:16 sc1 nt
.LBB0_100:
	v_or_b32_e32 v78, 6, v22
	v_mad_i64_i32 v[78:79], s[30:31], v78, s28, v[24:25]
	global_load_dword v78, v[78:79], off sc1 nt
	s_and_b64 vcc, exec, s[4:5]
	s_cbranch_vccnz .LBB0_102
	global_load_dword v76, v[26:27], off offset:24 sc1 nt
.LBB0_102:
	v_or_b32_e32 v79, 8, v22
	v_mad_i64_i32 v[80:81], s[30:31], v79, s28, v[24:25]
	global_load_dword v79, v[80:81], off sc1 nt
	v_mov_b32_e32 v80, 1.0
	s_and_b64 vcc, exec, s[4:5]
	v_mov_b32_e32 v81, 1.0
	s_cbranch_vccnz .LBB0_104
	global_load_dword v81, v[26:27], off offset:32 sc1 nt
.LBB0_104:
	v_or_b32_e32 v82, 10, v22
	v_mad_i64_i32 v[82:83], s[30:31], v82, s28, v[24:25]
	global_load_dword v82, v[82:83], off sc1 nt
	s_and_b64 vcc, exec, s[4:5]
	s_cbranch_vccnz .LBB0_106
	global_load_dword v80, v[26:27], off offset:40 sc1 nt
.LBB0_106:
	v_or_b32_e32 v83, 12, v22
	v_mad_i64_i32 v[84:85], s[30:31], v83, s28, v[24:25]
	global_load_dword v83, v[84:85], off sc1 nt
	v_mov_b32_e32 v84, 1.0
	s_and_b64 vcc, exec, s[4:5]
	v_mov_b32_e32 v85, 1.0
	s_cbranch_vccnz .LBB0_108
	global_load_dword v85, v[26:27], off offset:48 sc1 nt
.LBB0_108:
	v_or_b32_e32 v86, 14, v22
	v_mad_i64_i32 v[86:87], s[30:31], v86, s28, v[24:25]
	global_load_dword v86, v[86:87], off sc1 nt
	s_and_b64 vcc, exec, s[4:5]
	s_cbranch_vccnz .LBB0_110
	global_load_dword v84, v[26:27], off offset:56 sc1 nt
.LBB0_110:
	v_or_b32_e32 v87, 16, v22
	v_mad_i64_i32 v[88:89], s[30:31], v87, s28, v[24:25]
	global_load_dword v87, v[88:89], off sc1 nt
	v_mov_b32_e32 v88, 1.0
	s_and_b64 vcc, exec, s[4:5]
	v_mov_b32_e32 v89, 1.0
	s_cbranch_vccnz .LBB0_112
	global_load_dword v89, v[26:27], off offset:64 sc1 nt
.LBB0_112:
	v_or_b32_e32 v90, 18, v22
	v_mad_i64_i32 v[90:91], s[30:31], v90, s28, v[24:25]
	global_load_dword v90, v[90:91], off sc1 nt
	s_and_b64 vcc, exec, s[4:5]
	s_cbranch_vccnz .LBB0_114
	global_load_dword v88, v[26:27], off offset:72 sc1 nt
.LBB0_114:
	v_or_b32_e32 v91, 20, v22
	v_mad_i64_i32 v[92:93], s[30:31], v91, s28, v[24:25]
	global_load_dword v91, v[92:93], off sc1 nt
	v_mov_b32_e32 v92, 1.0
	s_and_b64 vcc, exec, s[4:5]
	v_mov_b32_e32 v93, 1.0
	s_cbranch_vccnz .LBB0_116
	global_load_dword v93, v[26:27], off offset:80 sc1 nt
.LBB0_116:
	v_or_b32_e32 v94, 22, v22
	v_mad_i64_i32 v[94:95], s[30:31], v94, s28, v[24:25]
	global_load_dword v94, v[94:95], off sc1 nt
	s_and_b64 vcc, exec, s[4:5]
	s_cbranch_vccnz .LBB0_118
	global_load_dword v92, v[26:27], off offset:88 sc1 nt
.LBB0_118:
	v_or_b32_e32 v95, 24, v22
	v_mad_i64_i32 v[96:97], s[30:31], v95, s28, v[24:25]
	global_load_dword v95, v[96:97], off sc1 nt
	v_mov_b32_e32 v96, 1.0
	s_and_b64 vcc, exec, s[4:5]
	v_mov_b32_e32 v97, 1.0
	s_cbranch_vccnz .LBB0_120
	global_load_dword v97, v[26:27], off offset:96 sc1 nt
.LBB0_120:
	v_or_b32_e32 v98, 26, v22
	v_mad_i64_i32 v[98:99], s[30:31], v98, s28, v[24:25]
	global_load_dword v98, v[98:99], off sc1 nt
	s_and_b64 vcc, exec, s[4:5]
	s_cbranch_vccnz .LBB0_122
	global_load_dword v96, v[26:27], off offset:104 sc1 nt
.LBB0_122:
	v_or_b32_e32 v99, 28, v22
	v_mad_i64_i32 v[100:101], s[30:31], v99, s28, v[24:25]
	global_load_dword v99, v[100:101], off sc1 nt
	v_mov_b32_e32 v100, 1.0
	s_and_b64 vcc, exec, s[4:5]
	v_mov_b32_e32 v101, 1.0
	s_cbranch_vccnz .LBB0_124
	global_load_dword v101, v[26:27], off offset:112 sc1 nt
.LBB0_124:
	v_or_b32_e32 v102, 30, v22
	v_mad_i64_i32 v[102:103], s[30:31], v102, s28, v[24:25]
	global_load_dword v102, v[102:103], off sc1 nt
	s_and_b64 vcc, exec, s[4:5]
	s_cbranch_vccnz .LBB0_126
	global_load_dword v100, v[26:27], off offset:120 sc1 nt
.LBB0_126:
	v_or_b32_e32 v103, 32, v22
	v_mad_i64_i32 v[104:105], s[30:31], v103, s28, v[24:25]
	global_load_dword v103, v[104:105], off sc1 nt
	v_mov_b32_e32 v104, 1.0
	s_and_b64 vcc, exec, s[4:5]
	v_mov_b32_e32 v105, 1.0
	s_cbranch_vccnz .LBB0_128
	global_load_dword v105, v[26:27], off offset:128 sc1 nt
.LBB0_128:
	v_or_b32_e32 v106, 34, v22
	v_mad_i64_i32 v[106:107], s[30:31], v106, s28, v[24:25]
	global_load_dword v106, v[106:107], off sc1 nt
	s_and_b64 vcc, exec, s[4:5]
	s_cbranch_vccnz .LBB0_130
	global_load_dword v104, v[26:27], off offset:136 sc1 nt
.LBB0_130:
	v_or_b32_e32 v107, 36, v22
	v_mad_i64_i32 v[108:109], s[30:31], v107, s28, v[24:25]
	global_load_dword v107, v[108:109], off sc1 nt
	v_mov_b32_e32 v108, 1.0
	s_and_b64 vcc, exec, s[4:5]
	v_mov_b32_e32 v109, 1.0
	s_cbranch_vccnz .LBB0_132
	global_load_dword v109, v[26:27], off offset:144 sc1 nt
.LBB0_132:
	v_or_b32_e32 v110, 38, v22
	v_mad_i64_i32 v[110:111], s[30:31], v110, s28, v[24:25]
	global_load_dword v110, v[110:111], off sc1 nt
	s_and_b64 vcc, exec, s[4:5]
	s_cbranch_vccnz .LBB0_134
	global_load_dword v108, v[26:27], off offset:152 sc1 nt
.LBB0_134:
	v_or_b32_e32 v111, 40, v22
	v_mad_i64_i32 v[112:113], s[30:31], v111, s28, v[24:25]
	global_load_dword v111, v[112:113], off sc1 nt
	v_mov_b32_e32 v112, 1.0
	s_and_b64 vcc, exec, s[4:5]
	v_mov_b32_e32 v113, 1.0
	s_cbranch_vccnz .LBB0_136
	global_load_dword v113, v[26:27], off offset:160 sc1 nt
.LBB0_136:
	v_or_b32_e32 v114, 42, v22
	v_mad_i64_i32 v[114:115], s[30:31], v114, s28, v[24:25]
	global_load_dword v114, v[114:115], off sc1 nt
	s_and_b64 vcc, exec, s[4:5]
	s_cbranch_vccnz .LBB0_138
	global_load_dword v112, v[26:27], off offset:168 sc1 nt
.LBB0_138:
	v_or_b32_e32 v115, 44, v22
	v_mad_i64_i32 v[116:117], s[30:31], v115, s28, v[24:25]
	global_load_dword v115, v[116:117], off sc1 nt
	v_mov_b32_e32 v116, 1.0
	s_and_b64 vcc, exec, s[4:5]
	v_mov_b32_e32 v117, 1.0
	s_cbranch_vccnz .LBB0_140
	global_load_dword v117, v[26:27], off offset:176 sc1 nt
.LBB0_140:
	v_or_b32_e32 v118, 46, v22
	v_mad_i64_i32 v[118:119], s[30:31], v118, s28, v[24:25]
	global_load_dword v118, v[118:119], off sc1 nt
	s_and_b64 vcc, exec, s[4:5]
	s_cbranch_vccnz .LBB0_142
	global_load_dword v116, v[26:27], off offset:184 sc1 nt
.LBB0_142:
	v_or_b32_e32 v119, 48, v22
	v_mad_i64_i32 v[120:121], s[30:31], v119, s28, v[24:25]
	global_load_dword v119, v[120:121], off sc1 nt
	v_mov_b32_e32 v120, 1.0
	s_and_b64 vcc, exec, s[4:5]
	v_mov_b32_e32 v121, 1.0
	s_cbranch_vccnz .LBB0_144
	global_load_dword v121, v[26:27], off offset:192 sc1 nt
.LBB0_144:
	v_or_b32_e32 v122, 50, v22
	v_mad_i64_i32 v[122:123], s[30:31], v122, s28, v[24:25]
	global_load_dword v122, v[122:123], off sc1 nt
	s_and_b64 vcc, exec, s[4:5]
	s_cbranch_vccnz .LBB0_146
	global_load_dword v120, v[26:27], off offset:200 sc1 nt
.LBB0_146:
	v_or_b32_e32 v123, 52, v22
	v_mad_i64_i32 v[124:125], s[30:31], v123, s28, v[24:25]
	global_load_dword v123, v[124:125], off sc1 nt
	v_mov_b32_e32 v124, 1.0
	s_and_b64 vcc, exec, s[4:5]
	v_mov_b32_e32 v125, 1.0
	s_cbranch_vccnz .LBB0_148
	global_load_dword v125, v[26:27], off offset:208 sc1 nt
.LBB0_148:
	v_or_b32_e32 v126, 54, v22
	v_mad_i64_i32 v[126:127], s[30:31], v126, s28, v[24:25]
	global_load_dword v126, v[126:127], off sc1 nt
	s_and_b64 vcc, exec, s[4:5]
	s_cbranch_vccnz .LBB0_150
	global_load_dword v124, v[26:27], off offset:216 sc1 nt
.LBB0_150:
	v_or_b32_e32 v127, 56, v22
	v_mad_i64_i32 v[128:129], s[30:31], v127, s28, v[24:25]
	global_load_dword v127, v[128:129], off sc1 nt
	v_mov_b32_e32 v128, 1.0
	s_and_b64 vcc, exec, s[4:5]
	v_mov_b32_e32 v129, 1.0
	s_cbranch_vccnz .LBB0_152
	global_load_dword v129, v[26:27], off offset:224 sc1 nt
.LBB0_152:
	v_or_b32_e32 v130, 58, v22
	v_mad_i64_i32 v[130:131], s[30:31], v130, s28, v[24:25]
	global_load_dword v130, v[130:131], off sc1 nt
	s_and_b64 vcc, exec, s[4:5]
	s_cbranch_vccnz .LBB0_154
	global_load_dword v128, v[26:27], off offset:232 sc1 nt
.LBB0_154:
	v_or_b32_e32 v131, 60, v22
	v_mad_i64_i32 v[132:133], s[30:31], v131, s28, v[24:25]
	global_load_dword v131, v[132:133], off sc1 nt
	v_mov_b32_e32 v132, 1.0
	s_and_b64 vcc, exec, s[4:5]
	v_mov_b32_e32 v133, 1.0
	s_cbranch_vccnz .LBB0_156
	global_load_dword v133, v[26:27], off offset:240 sc1 nt
.LBB0_156:
	v_or_b32_e32 v22, 62, v22
	v_mad_i64_i32 v[24:25], s[30:31], v22, s28, v[24:25]
	global_load_dword v22, v[24:25], off sc1 nt
	s_and_b64 vcc, exec, s[4:5]
	s_cbranch_vccnz .LBB0_13
	global_load_dword v132, v[26:27], off offset:248 sc1 nt
	s_branch .LBB0_13

.LBB0_161:
	s_waitcnt lgkmcnt(0)
	global_load_dwordx4 v[12:15], v[4:5], off offset:-3072 sc1 nt
	global_load_dwordx4 v[16:19], v[4:5], off offset:-2048 sc1 nt
	global_load_dwordx4 v[20:23], v[4:5], off offset:-1024 sc1 nt
	global_load_dwordx4 v[24:27], v[4:5], off sc1 nt
	s_waitcnt vmcnt(3)
	v_mul_f32_e32 v2, v13, v13
	v_mul_f32_e32 v28, v15, v15
	s_waitcnt vmcnt(2)
	v_mul_f32_e32 v29, v17, v17
	v_mul_f32_e32 v30, v19, v19
	s_waitcnt vmcnt(1)
	v_mul_f32_e32 v31, v21, v21
	v_mul_f32_e32 v32, v23, v23
	v_fmac_f32_e32 v2, v12, v12
	v_fmac_f32_e32 v28, v14, v14
	v_fmac_f32_e32 v29, v16, v16
	v_fmac_f32_e32 v30, v18, v18
	s_waitcnt vmcnt(0)
	v_mul_f32_e32 v33, v25, v25
	v_mul_f32_e32 v34, v27, v27
	v_fmac_f32_e32 v31, v20, v20
	v_fmac_f32_e32 v32, v22, v22
	v_add_f32_e32 v2, v2, v28
	v_add_f32_e32 v28, v29, v30
	v_fmac_f32_e32 v33, v24, v24
	v_fmac_f32_e32 v34, v26, v26
	v_add_f32_e32 v29, v31, v32
	v_add_f32_e32 v2, v2, v28
	v_add_f32_e32 v30, v33, v34
	v_add_f32_e32 v2, v2, v29
	v_add_f32_e32 v2, v2, v30
	ds_bpermute_b32 v28, v6, v2
	v_cvt_pk_bf16_f32 v12, v12, v13
	v_cvt_pk_bf16_f32 v13, v14, v15
	v_cvt_pk_bf16_f32 v14, v16, v17
	v_cvt_pk_bf16_f32 v15, v18, v19
	s_waitcnt lgkmcnt(0)
	v_add_f32_e32 v2, v2, v28
	ds_bpermute_b32 v28, v7, v2
	v_cvt_pk_bf16_f32 v16, v20, v21
	s_waitcnt lgkmcnt(0)
	v_add_f32_e32 v2, v2, v28
	ds_bpermute_b32 v30, v8, v2
	v_lshl_add_u64 v[28:29], s[96:97], 0, v[0:1]
	v_add_co_u32_e64 v28, s[0:1], s9, v28
	s_waitcnt lgkmcnt(0)
	v_add_f32_e32 v2, v2, v30
	ds_bpermute_b32 v30, v9, v2
	v_addc_co_u32_e64 v29, s[0:1], 0, v29, s[0:1]
	global_store_dwordx2 v[28:29], v[12:13], off
	global_store_dwordx2 v[28:29], v[14:15], off offset:512
	v_cvt_pk_bf16_f32 v14, v24, v25
	s_waitcnt lgkmcnt(0)
	v_add_f32_e32 v2, v2, v30
	ds_bpermute_b32 v17, v10, v2
	v_cvt_pk_bf16_f32 v15, v26, v27
	global_store_dwordx2 v[28:29], v[14:15], off offset:1536
	s_waitcnt lgkmcnt(0)
	v_add_f32_e32 v2, v2, v17
	ds_bpermute_b32 v12, v11, v2
	v_cvt_pk_bf16_f32 v17, v22, v23
	global_store_dwordx2 v[28:29], v[16:17], off offset:1024
	s_and_saveexec_b64 s[0:1], vcc
	s_cbranch_execz .LBB0_160
	s_add_u32 s16, s96, s2
	s_addc_u32 s17, s97, s3
	s_waitcnt lgkmcnt(0)
	v_add_f32_e32 v2, v2, v12
	global_store_dword v3, v2, s[16:17]
	s_branch .LBB0_160

.LBB0_836:
	s_cmpk_gt_i32 s8, 0x7ff
	s_mov_b64 s[4:5], -1
	s_cbranch_scc0 .LBB0_842
	s_and_b32 s6, s10, 0x3e0
	s_cmpk_gt_u32 s8, 0x9ff
	v_or_b32_e32 v17, s6, v19
	v_or_b32_e32 v16, s6, v21
	v_or_b32_e32 v15, s6, v22
	v_or_b32_e32 v14, s6, v23
	s_cbranch_scc0 .LBB0_839
	s_and_b32 s4, s12, 0x1ffc0
	v_or_b32_e32 v0, s4, v229
	s_lshl_b32 s0, s6, 2
	v_lshl_add_u64 v[32:33], v[4:5], 0, s[0:1]
	v_lshlrev_b32_e32 v0, 12, v0
	v_lshl_add_u64 v[32:33], v[32:33], 0, v[0:1]
	v_add_co_u32_e32 v34, vcc, 0x2000, v32
	s_lshl_b32 s0, s4, 1
	s_nop 0
	v_addc_co_u32_e32 v35, vcc, 0, v33, vcc
	v_add_co_u32_e32 v36, vcc, 0x4000, v32
	s_mov_b64 s[4:5], 0
	s_nop 0
	v_addc_co_u32_e32 v37, vcc, 0, v33, vcc
	v_add_co_u32_e32 v38, vcc, 0x6000, v32
	s_nop 1
	v_addc_co_u32_e32 v39, vcc, 0, v33, vcc
	v_add_co_u32_e32 v40, vcc, 0x8000, v32
	s_nop 1
	v_addc_co_u32_e32 v41, vcc, 0, v33, vcc
	v_add_co_u32_e32 v42, vcc, 0xa000, v32
	s_nop 1
	v_addc_co_u32_e32 v43, vcc, 0, v33, vcc
	v_add_co_u32_e32 v44, vcc, 0xc000, v32
	s_nop 1
	v_addc_co_u32_e32 v45, vcc, 0, v33, vcc
	v_add_co_u32_e32 v46, vcc, 0xe000, v32
	s_nop 1
	v_addc_co_u32_e32 v47, vcc, 0, v33, vcc
	global_load_dword v0, v[32:33], off sc1 nt
	global_load_dword v31, v[34:35], off sc1 nt
	global_load_dword v50, v[36:37], off sc1 nt
	global_load_dword v51, v[38:39], off sc1 nt
	global_load_dword v52, v[40:41], off sc1 nt
	global_load_dword v53, v[42:43], off sc1 nt
	global_load_dword v54, v[44:45], off sc1 nt
	global_load_dword v55, v[46:47], off sc1 nt
	v_add_co_u32_e32 v34, vcc, 0x10000, v32
	s_nop 1
	v_addc_co_u32_e32 v35, vcc, 0, v33, vcc
	v_add_co_u32_e32 v36, vcc, 0x12000, v32
	s_nop 1
	v_addc_co_u32_e32 v37, vcc, 0, v33, vcc
	v_add_co_u32_e32 v38, vcc, 0x14000, v32
	s_nop 1
	v_addc_co_u32_e32 v39, vcc, 0, v33, vcc
	v_add_co_u32_e32 v40, vcc, 0x16000, v32
	s_nop 1
	v_addc_co_u32_e32 v41, vcc, 0, v33, vcc
	v_add_co_u32_e32 v42, vcc, 0x18000, v32
	s_nop 1
	v_addc_co_u32_e32 v43, vcc, 0, v33, vcc
	v_add_co_u32_e32 v44, vcc, 0x1a000, v32
	s_nop 1
	v_addc_co_u32_e32 v45, vcc, 0, v33, vcc
	v_add_co_u32_e32 v46, vcc, 0x1c000, v32
	s_nop 1
	v_addc_co_u32_e32 v47, vcc, 0, v33, vcc
	v_add_co_u32_e32 v48, vcc, 0x1e000, v32
	s_nop 1
	v_addc_co_u32_e32 v49, vcc, 0, v33, vcc
	global_load_dword v56, v[34:35], off sc1 nt
	global_load_dword v57, v[36:37], off sc1 nt
	global_load_dword v58, v[38:39], off sc1 nt
	global_load_dword v59, v[40:41], off sc1 nt
	global_load_dword v60, v[42:43], off sc1 nt
	global_load_dword v61, v[44:45], off sc1 nt
	global_load_dword v62, v[46:47], off sc1 nt
	global_load_dword v63, v[48:49], off sc1 nt
	v_add_co_u32_e32 v34, vcc, 0x20000, v32
	s_nop 1
	v_addc_co_u32_e32 v35, vcc, 0, v33, vcc
	v_add_co_u32_e32 v36, vcc, 0x22000, v32
	s_nop 1
	v_addc_co_u32_e32 v37, vcc, 0, v33, vcc
	v_add_co_u32_e32 v38, vcc, 0x24000, v32
	s_nop 1
	v_addc_co_u32_e32 v39, vcc, 0, v33, vcc
	v_add_co_u32_e32 v40, vcc, 0x26000, v32
	s_nop 1
	v_addc_co_u32_e32 v41, vcc, 0, v33, vcc
	v_add_co_u32_e32 v42, vcc, 0x28000, v32
	s_nop 1
	v_addc_co_u32_e32 v43, vcc, 0, v33, vcc
	v_add_co_u32_e32 v44, vcc, 0x2a000, v32
	s_nop 1
	v_addc_co_u32_e32 v45, vcc, 0, v33, vcc
	v_add_co_u32_e32 v46, vcc, 0x2c000, v32
	s_nop 1
	v_addc_co_u32_e32 v47, vcc, 0, v33, vcc
	v_add_co_u32_e32 v48, vcc, 0x2e000, v32
	s_nop 1
	v_addc_co_u32_e32 v49, vcc, 0, v33, vcc
	global_load_dword v64, v[34:35], off sc1 nt
	global_load_dword v65, v[36:37], off sc1 nt
	global_load_dword v66, v[38:39], off sc1 nt
	global_load_dword v67, v[40:41], off sc1 nt
	global_load_dword v68, v[42:43], off sc1 nt
	global_load_dword v69, v[44:45], off sc1 nt
	global_load_dword v70, v[46:47], off sc1 nt
	s_nop 0
	global_load_dword v48, v[48:49], off sc1 nt
	v_add_co_u32_e32 v34, vcc, 0x30000, v32
	s_nop 1
	v_addc_co_u32_e32 v35, vcc, 0, v33, vcc
	v_add_co_u32_e32 v36, vcc, 0x32000, v32
	s_nop 1
	v_addc_co_u32_e32 v37, vcc, 0, v33, vcc
	v_add_co_u32_e32 v38, vcc, 0x34000, v32
	s_nop 1
	v_addc_co_u32_e32 v39, vcc, 0, v33, vcc
	v_add_co_u32_e32 v40, vcc, 0x36000, v32
	s_nop 1
	v_addc_co_u32_e32 v41, vcc, 0, v33, vcc
	v_add_co_u32_e32 v42, vcc, 0x38000, v32
	s_nop 1
	v_addc_co_u32_e32 v43, vcc, 0, v33, vcc
	v_add_co_u32_e32 v44, vcc, 0x3a000, v32
	s_nop 1
	v_addc_co_u32_e32 v45, vcc, 0, v33, vcc
	v_add_co_u32_e32 v46, vcc, 0x3c000, v32
	s_nop 1
	v_addc_co_u32_e32 v47, vcc, 0, v33, vcc
	v_add_co_u32_e32 v32, vcc, 0x3e000, v32
	s_nop 1
	v_addc_co_u32_e32 v33, vcc, 0, v33, vcc
	global_load_dword v34, v[34:35], off sc1 nt
	s_nop 0
	global_load_dword v35, v[36:37], off sc1 nt
	s_nop 0
	global_load_dword v36, v[38:39], off sc1 nt
	global_load_dword v37, v[40:41], off sc1 nt
	s_nop 0
	global_load_dword v38, v[42:43], off sc1 nt
	global_load_dword v39, v[44:45], off sc1 nt
	global_load_dword v40, v[46:47], off sc1 nt
	s_nop 0
	global_load_dword v32, v[32:33], off sc1 nt
	s_waitcnt vmcnt(30)
	ds_write2_b32 v18, v0, v31 offset1:66
	s_waitcnt vmcnt(28)
	ds_write2_b32 v18, v50, v51 offset0:132 offset1:198
	s_waitcnt vmcnt(26)
	ds_write2_b32 v24, v52, v53 offset0:8 offset1:74
	s_waitcnt vmcnt(24)
	ds_write2_b32 v24, v54, v55 offset0:140 offset1:206
	s_waitcnt vmcnt(22)
	ds_write2_b32 v25, v56, v57 offset0:16 offset1:82
	s_waitcnt vmcnt(20)
	ds_write2_b32 v25, v58, v59 offset0:148 offset1:214
	s_waitcnt vmcnt(18)
	ds_write2_b32 v26, v60, v61 offset0:24 offset1:90
	s_waitcnt vmcnt(16)
	ds_write2_b32 v26, v62, v63 offset0:156 offset1:222
	s_waitcnt vmcnt(14)
	ds_write2_b32 v27, v64, v65 offset0:32 offset1:98
	s_waitcnt vmcnt(12)
	ds_write2_b32 v27, v66, v67 offset0:164 offset1:230
	s_waitcnt vmcnt(10)
	ds_write2_b32 v28, v68, v69 offset0:40 offset1:106
	s_waitcnt vmcnt(8)
	ds_write2_b32 v28, v70, v48 offset0:172 offset1:238
	s_waitcnt vmcnt(6)
	ds_write2_b32 v29, v34, v35 offset0:48 offset1:114
	s_waitcnt vmcnt(4)
	ds_write2_b32 v29, v36, v37 offset0:180 offset1:246
	s_waitcnt vmcnt(2)
	ds_write2_b32 v30, v38, v39 offset0:56 offset1:122
	s_waitcnt vmcnt(0)
	ds_write2_b32 v30, v40, v32 offset0:188 offset1:254
	s_waitcnt lgkmcnt(0)
	ds_read2_b32 v[36:37], v20 offset0:33 offset1:41
	ds_read2_b32 v[38:39], v20 offset1:8
	ds_read2_b32 v[40:41], v20 offset0:66 offset1:74
	ds_read2_b32 v[42:43], v20 offset0:99 offset1:107
	ds_read2_b32 v[44:45], v20 offset0:132 offset1:140
	ds_read2_b32 v[46:47], v20 offset0:165 offset1:173
	ds_read2_b32 v[48:49], v20 offset0:198 offset1:206
	ds_read2_b32 v[50:51], v20 offset0:231 offset1:239
	v_lshl_add_u64 v[52:53], v[6:7], 0, s[0:1]
	v_lshlrev_b32_e32 v0, 13, v17
	s_waitcnt lgkmcnt(6)
	v_cvt_pk_bf16_f32 v32, v38, v36
	s_waitcnt lgkmcnt(4)
	v_cvt_pk_bf16_f32 v33, v40, v42
	s_waitcnt lgkmcnt(2)
	v_cvt_pk_bf16_f32 v34, v44, v46
	s_waitcnt lgkmcnt(0)
	v_cvt_pk_bf16_f32 v35, v48, v50
	v_lshl_add_u64 v[54:55], v[52:53], 0, v[0:1]
	global_store_dwordx4 v[54:55], v[32:35], off
	v_lshlrev_b32_e32 v0, 13, v16
	s_nop 0
	v_cvt_pk_bf16_f32 v32, v39, v37
	v_cvt_pk_bf16_f32 v33, v41, v43
	v_cvt_pk_bf16_f32 v34, v45, v47
	v_cvt_pk_bf16_f32 v35, v49, v51
	ds_read2_b32 v[38:39], v20 offset0:49 offset1:57
	ds_read2_b32 v[40:41], v20 offset0:16 offset1:24
	ds_read2_b32 v[42:43], v20 offset0:82 offset1:90
	ds_read2_b32 v[44:45], v20 offset0:115 offset1:123
	ds_read2_b32 v[46:47], v20 offset0:148 offset1:156
	ds_read2_b32 v[48:49], v20 offset0:181 offset1:189
	ds_read2_b32 v[50:51], v20 offset0:214 offset1:222
	ds_read2_b32 v[54:55], v20 offset0:247 offset1:255
	v_lshl_add_u64 v[36:37], v[52:53], 0, v[0:1]
	v_lshlrev_b32_e32 v0, 13, v15
	global_store_dwordx4 v[36:37], v[32:35], off
	v_lshl_add_u64 v[36:37], v[52:53], 0, v[0:1]
	v_lshlrev_b32_e32 v0, 13, v14
	s_waitcnt lgkmcnt(6)
	v_cvt_pk_bf16_f32 v32, v40, v38
	s_waitcnt lgkmcnt(4)
	v_cvt_pk_bf16_f32 v33, v42, v44
	s_waitcnt lgkmcnt(2)
	v_cvt_pk_bf16_f32 v34, v46, v48
	s_waitcnt lgkmcnt(0)
	v_cvt_pk_bf16_f32 v35, v50, v54
	global_store_dwordx4 v[36:37], v[32:35], off
	v_lshl_add_u64 v[36:37], v[52:53], 0, v[0:1]
	s_nop 0
	v_cvt_pk_bf16_f32 v32, v41, v39
	v_cvt_pk_bf16_f32 v33, v43, v45
	v_cvt_pk_bf16_f32 v34, v47, v49
	v_cvt_pk_bf16_f32 v35, v51, v55
	global_store_dwordx4 v[36:37], v[32:35], off
	s_waitcnt lgkmcnt(0)
.LBB0_839:
	s_andn2_b64 vcc, exec, s[4:5]
	s_cbranch_vccnz .LBB0_841
	s_add_i32 s0, s12, 0x400
	s_and_b32 s4, s0, 0x1ffc0
	v_or_b32_e32 v0, s4, v229
	s_lshl_b32 s0, s6, 2
	v_lshl_add_u64 v[32:33], v[2:3], 0, s[0:1]
	v_lshlrev_b32_e32 v0, 12, v0
	v_lshl_add_u64 v[32:33], v[32:33], 0, v[0:1]
	v_add_co_u32_e32 v34, vcc, 0x2000, v32
	s_lshl_b32 s0, s4, 1
	s_nop 0
	v_addc_co_u32_e32 v35, vcc, 0, v33, vcc
	v_add_co_u32_e32 v36, vcc, 0x4000, v32
	s_nop 1
	v_addc_co_u32_e32 v37, vcc, 0, v33, vcc
	v_add_co_u32_e32 v38, vcc, 0x6000, v32
	s_nop 1
	v_addc_co_u32_e32 v39, vcc, 0, v33, vcc
	v_add_co_u32_e32 v40, vcc, 0x8000, v32
	s_nop 1
	v_addc_co_u32_e32 v41, vcc, 0, v33, vcc
	v_add_co_u32_e32 v42, vcc, 0xa000, v32
	s_nop 1
	v_addc_co_u32_e32 v43, vcc, 0, v33, vcc
	v_add_co_u32_e32 v44, vcc, 0xc000, v32
	s_nop 1
	v_addc_co_u32_e32 v45, vcc, 0, v33, vcc
	v_add_co_u32_e32 v46, vcc, 0xe000, v32
	s_nop 1
	v_addc_co_u32_e32 v47, vcc, 0, v33, vcc
	global_load_dword v0, v[32:33], off sc1 nt
	global_load_dword v31, v[34:35], off sc1 nt
	global_load_dword v50, v[36:37], off sc1 nt
	global_load_dword v51, v[38:39], off sc1 nt
	global_load_dword v52, v[40:41], off sc1 nt
	global_load_dword v53, v[42:43], off sc1 nt
	global_load_dword v54, v[44:45], off sc1 nt
	global_load_dword v55, v[46:47], off sc1 nt
	v_add_co_u32_e32 v34, vcc, 0x10000, v32
	s_nop 1
	v_addc_co_u32_e32 v35, vcc, 0, v33, vcc
	v_add_co_u32_e32 v36, vcc, 0x12000, v32
	s_nop 1
	v_addc_co_u32_e32 v37, vcc, 0, v33, vcc
	v_add_co_u32_e32 v38, vcc, 0x14000, v32
	s_nop 1
	v_addc_co_u32_e32 v39, vcc, 0, v33, vcc
	v_add_co_u32_e32 v40, vcc, 0x16000, v32
	s_nop 1
	v_addc_co_u32_e32 v41, vcc, 0, v33, vcc
	v_add_co_u32_e32 v42, vcc, 0x18000, v32
	s_nop 1
	v_addc_co_u32_e32 v43, vcc, 0, v33, vcc
	v_add_co_u32_e32 v44, vcc, 0x1a000, v32
	s_nop 1
	v_addc_co_u32_e32 v45, vcc, 0, v33, vcc
	v_add_co_u32_e32 v46, vcc, 0x1c000, v32
	s_nop 1
	v_addc_co_u32_e32 v47, vcc, 0, v33, vcc
	v_add_co_u32_e32 v48, vcc, 0x1e000, v32
	s_nop 1
	v_addc_co_u32_e32 v49, vcc, 0, v33, vcc
	global_load_dword v56, v[34:35], off sc1 nt
	global_load_dword v57, v[36:37], off sc1 nt
	global_load_dword v58, v[38:39], off sc1 nt
	global_load_dword v59, v[40:41], off sc1 nt
	global_load_dword v60, v[42:43], off sc1 nt
	global_load_dword v61, v[44:45], off sc1 nt
	global_load_dword v62, v[46:47], off sc1 nt
	global_load_dword v63, v[48:49], off sc1 nt
	v_add_co_u32_e32 v34, vcc, 0x20000, v32
	s_nop 1
	v_addc_co_u32_e32 v35, vcc, 0, v33, vcc
	v_add_co_u32_e32 v36, vcc, 0x22000, v32
	s_nop 1
	v_addc_co_u32_e32 v37, vcc, 0, v33, vcc
	v_add_co_u32_e32 v38, vcc, 0x24000, v32
	s_nop 1
	v_addc_co_u32_e32 v39, vcc, 0, v33, vcc
	v_add_co_u32_e32 v40, vcc, 0x26000, v32
	s_nop 1
	v_addc_co_u32_e32 v41, vcc, 0, v33, vcc
	v_add_co_u32_e32 v42, vcc, 0x28000, v32
	s_nop 1
	v_addc_co_u32_e32 v43, vcc, 0, v33, vcc
	v_add_co_u32_e32 v44, vcc, 0x2a000, v32
	s_nop 1
	v_addc_co_u32_e32 v45, vcc, 0, v33, vcc
	v_add_co_u32_e32 v46, vcc, 0x2c000, v32
	s_nop 1
	v_addc_co_u32_e32 v47, vcc, 0, v33, vcc
	v_add_co_u32_e32 v48, vcc, 0x2e000, v32
	s_nop 1
	v_addc_co_u32_e32 v49, vcc, 0, v33, vcc
	global_load_dword v64, v[34:35], off sc1 nt
	global_load_dword v65, v[36:37], off sc1 nt
	global_load_dword v66, v[38:39], off sc1 nt
	global_load_dword v67, v[40:41], off sc1 nt
	global_load_dword v68, v[42:43], off sc1 nt
	global_load_dword v69, v[44:45], off sc1 nt
	global_load_dword v70, v[46:47], off sc1 nt
	s_nop 0
	global_load_dword v48, v[48:49], off sc1 nt
	v_add_co_u32_e32 v34, vcc, 0x30000, v32
	s_nop 1
	v_addc_co_u32_e32 v35, vcc, 0, v33, vcc
	v_add_co_u32_e32 v36, vcc, 0x32000, v32
	s_nop 1
	v_addc_co_u32_e32 v37, vcc, 0, v33, vcc
	v_add_co_u32_e32 v38, vcc, 0x34000, v32
	s_nop 1
	v_addc_co_u32_e32 v39, vcc, 0, v33, vcc
	v_add_co_u32_e32 v40, vcc, 0x36000, v32
	s_nop 1
	v_addc_co_u32_e32 v41, vcc, 0, v33, vcc
	v_add_co_u32_e32 v42, vcc, 0x38000, v32
	s_nop 1
	v_addc_co_u32_e32 v43, vcc, 0, v33, vcc
	v_add_co_u32_e32 v44, vcc, 0x3a000, v32
	s_nop 1
	v_addc_co_u32_e32 v45, vcc, 0, v33, vcc
	v_add_co_u32_e32 v46, vcc, 0x3c000, v32
	s_nop 1
	v_addc_co_u32_e32 v47, vcc, 0, v33, vcc
	v_add_co_u32_e32 v32, vcc, 0x3e000, v32
	s_nop 1
	v_addc_co_u32_e32 v33, vcc, 0, v33, vcc
	global_load_dword v34, v[34:35], off sc1 nt
	s_nop 0
	global_load_dword v35, v[36:37], off sc1 nt
	s_nop 0
	global_load_dword v36, v[38:39], off sc1 nt
	global_load_dword v37, v[40:41], off sc1 nt
	s_nop 0
	global_load_dword v38, v[42:43], off sc1 nt
	global_load_dword v39, v[44:45], off sc1 nt
	global_load_dword v40, v[46:47], off sc1 nt
	s_nop 0
	global_load_dword v32, v[32:33], off sc1 nt
	s_waitcnt vmcnt(30)
	ds_write2_b32 v18, v0, v31 offset1:66
	s_waitcnt vmcnt(28)
	ds_write2_b32 v18, v50, v51 offset0:132 offset1:198
	s_waitcnt vmcnt(26)
	ds_write2_b32 v24, v52, v53 offset0:8 offset1:74
	s_waitcnt vmcnt(24)
	ds_write2_b32 v24, v54, v55 offset0:140 offset1:206
	s_waitcnt vmcnt(22)
	ds_write2_b32 v25, v56, v57 offset0:16 offset1:82
	s_waitcnt vmcnt(20)
	ds_write2_b32 v25, v58, v59 offset0:148 offset1:214
	s_waitcnt vmcnt(18)
	ds_write2_b32 v26, v60, v61 offset0:24 offset1:90
	s_waitcnt vmcnt(16)
	ds_write2_b32 v26, v62, v63 offset0:156 offset1:222
	s_waitcnt vmcnt(14)
	ds_write2_b32 v27, v64, v65 offset0:32 offset1:98
	s_waitcnt vmcnt(12)
	ds_write2_b32 v27, v66, v67 offset0:164 offset1:230
	s_waitcnt vmcnt(10)
	ds_write2_b32 v28, v68, v69 offset0:40 offset1:106
	s_waitcnt vmcnt(8)
	ds_write2_b32 v28, v70, v48 offset0:172 offset1:238
	s_waitcnt vmcnt(6)
	ds_write2_b32 v29, v34, v35 offset0:48 offset1:114
	s_waitcnt vmcnt(4)
	ds_write2_b32 v29, v36, v37 offset0:180 offset1:246
	s_waitcnt vmcnt(2)
	ds_write2_b32 v30, v38, v39 offset0:56 offset1:122
	s_waitcnt vmcnt(0)
	ds_write2_b32 v30, v40, v32 offset0:188 offset1:254
	s_waitcnt lgkmcnt(0)
	ds_read2_b32 v[36:37], v20 offset0:33 offset1:41
	ds_read2_b32 v[38:39], v20 offset1:8
	ds_read2_b32 v[40:41], v20 offset0:66 offset1:74
	ds_read2_b32 v[42:43], v20 offset0:99 offset1:107
	ds_read2_b32 v[44:45], v20 offset0:132 offset1:140
	ds_read2_b32 v[46:47], v20 offset0:165 offset1:173
	ds_read2_b32 v[48:49], v20 offset0:198 offset1:206
	ds_read2_b32 v[50:51], v20 offset0:231 offset1:239
	v_lshl_add_u64 v[52:53], v[8:9], 0, s[0:1]
	v_lshlrev_b32_e32 v0, 11, v17
	s_waitcnt lgkmcnt(6)
	v_cvt_pk_bf16_f32 v32, v38, v36
	s_waitcnt lgkmcnt(4)
	v_cvt_pk_bf16_f32 v33, v40, v42
	s_waitcnt lgkmcnt(2)
	v_cvt_pk_bf16_f32 v34, v44, v46
	s_waitcnt lgkmcnt(0)
	v_cvt_pk_bf16_f32 v35, v48, v50
	v_lshl_add_u64 v[54:55], v[52:53], 0, v[0:1]
	global_store_dwordx4 v[54:55], v[32:35], off
	v_lshlrev_b32_e32 v0, 11, v16
	v_lshl_add_u64 v[16:17], v[52:53], 0, v[0:1]
	v_cvt_pk_bf16_f32 v32, v39, v37
	v_cvt_pk_bf16_f32 v33, v41, v43
	v_cvt_pk_bf16_f32 v34, v45, v47
	v_cvt_pk_bf16_f32 v35, v49, v51
	ds_read2_b32 v[36:37], v20 offset0:49 offset1:57
	ds_read2_b32 v[38:39], v20 offset0:16 offset1:24
	ds_read2_b32 v[40:41], v20 offset0:82 offset1:90
	ds_read2_b32 v[42:43], v20 offset0:115 offset1:123
	ds_read2_b32 v[44:45], v20 offset0:148 offset1:156
	ds_read2_b32 v[46:47], v20 offset0:181 offset1:189
	ds_read2_b32 v[48:49], v20 offset0:214 offset1:222
	ds_read2_b32 v[50:51], v20 offset0:247 offset1:255
	v_lshlrev_b32_e32 v0, 11, v15
	global_store_dwordx4 v[16:17], v[32:35], off
	v_lshl_add_u64 v[16:17], v[52:53], 0, v[0:1]
	v_lshlrev_b32_e32 v0, 11, v14
	s_waitcnt lgkmcnt(6)
	v_cvt_pk_bf16_f32 v32, v38, v36
	s_waitcnt lgkmcnt(4)
	v_cvt_pk_bf16_f32 v33, v40, v42
	s_waitcnt lgkmcnt(2)
	v_cvt_pk_bf16_f32 v34, v44, v46
	s_waitcnt lgkmcnt(0)
	v_cvt_pk_bf16_f32 v35, v48, v50
	global_store_dwordx4 v[16:17], v[32:35], off
	v_lshl_add_u64 v[14:15], v[52:53], 0, v[0:1]
	s_nop 0
	v_cvt_pk_bf16_f32 v32, v39, v37
	v_cvt_pk_bf16_f32 v33, v41, v43
	v_cvt_pk_bf16_f32 v34, v45, v47
	v_cvt_pk_bf16_f32 v35, v49, v51
	global_store_dwordx4 v[14:15], v[32:35], off
	s_waitcnt lgkmcnt(0)

.LBB0_842:
	s_andn2_b64 vcc, exec, s[4:5]
	s_cbranch_vccnz .LBB0_835
	s_ashr_i32 s0, s8, 31
	s_lshr_b32 s0, s0, 25
	s_add_i32 s0, s8, s0
	s_ashr_i32 s0, s0, 7
	s_lshl_b32 s6, s0, 6
	s_lshl_b32 s0, s0, 12
	s_sub_i32 s4, s10, s0
	v_or_b32_e32 v16, s6, v229
	s_ashr_i32 s5, s4, 31
	v_ashrrev_i32_e32 v17, 31, v16
	v_lshl_add_u64 v[14:15], s[4:5], 2, v[10:11]
	v_lshlrev_b64 v[32:33], 14, v[16:17]
	v_lshl_add_u64 v[32:33], v[14:15], 0, v[32:33]
	global_load_dword v0, v[32:33], off sc1 nt
	v_lshl_add_u64 v[32:33], v[16:17], 2, s[2:3]
	global_load_dword v31, v[32:33], off sc1 nt
	v_or_b32_e32 v32, 2, v16
	v_ashrrev_i32_e32 v33, 31, v32
	v_lshlrev_b64 v[34:35], 14, v[32:33]
	v_lshl_add_u64 v[32:33], v[32:33], 2, s[2:3]
	global_load_dword v37, v[32:33], off sc1 nt
	v_or_b32_e32 v32, 4, v16
	v_lshl_add_u64 v[34:35], v[14:15], 0, v[34:35]
	v_ashrrev_i32_e32 v33, 31, v32
	global_load_dword v36, v[34:35], off sc1 nt
	v_lshlrev_b64 v[34:35], 14, v[32:33]
	v_lshl_add_u64 v[32:33], v[32:33], 2, s[2:3]
	global_load_dword v39, v[32:33], off sc1 nt
	v_or_b32_e32 v32, 6, v16
	v_lshl_add_u64 v[34:35], v[14:15], 0, v[34:35]
	v_ashrrev_i32_e32 v33, 31, v32
	global_load_dword v38, v[34:35], off sc1 nt
	v_lshlrev_b64 v[34:35], 14, v[32:33]
	v_lshl_add_u64 v[32:33], v[32:33], 2, s[2:3]
	global_load_dword v41, v[32:33], off sc1 nt
	v_or_b32_e32 v32, 8, v16
	v_lshl_add_u64 v[34:35], v[14:15], 0, v[34:35]
	v_ashrrev_i32_e32 v33, 31, v32
	global_load_dword v40, v[34:35], off sc1 nt
	v_lshlrev_b64 v[34:35], 14, v[32:33]
	v_lshl_add_u64 v[32:33], v[32:33], 2, s[2:3]
	global_load_dword v43, v[32:33], off sc1 nt
	v_or_b32_e32 v32, 10, v16
	v_lshl_add_u64 v[34:35], v[14:15], 0, v[34:35]
	v_ashrrev_i32_e32 v33, 31, v32
	global_load_dword v42, v[34:35], off sc1 nt
	v_lshlrev_b64 v[34:35], 14, v[32:33]
	v_lshl_add_u64 v[32:33], v[32:33], 2, s[2:3]
	global_load_dword v45, v[32:33], off sc1 nt
	v_or_b32_e32 v32, 12, v16
	v_lshl_add_u64 v[34:35], v[14:15], 0, v[34:35]
	v_ashrrev_i32_e32 v33, 31, v32
	global_load_dword v44, v[34:35], off sc1 nt
	v_lshlrev_b64 v[34:35], 14, v[32:33]
	v_lshl_add_u64 v[32:33], v[32:33], 2, s[2:3]
	global_load_dword v47, v[32:33], off sc1 nt
	v_or_b32_e32 v32, 14, v16
	v_lshl_add_u64 v[34:35], v[14:15], 0, v[34:35]
	v_ashrrev_i32_e32 v33, 31, v32
	global_load_dword v46, v[34:35], off sc1 nt
	v_lshlrev_b64 v[34:35], 14, v[32:33]
	v_lshl_add_u64 v[32:33], v[32:33], 2, s[2:3]
	global_load_dword v49, v[32:33], off sc1 nt
	v_or_b32_e32 v32, 16, v16
	v_lshl_add_u64 v[34:35], v[14:15], 0, v[34:35]
	v_ashrrev_i32_e32 v33, 31, v32
	global_load_dword v48, v[34:35], off sc1 nt
	v_lshlrev_b64 v[34:35], 14, v[32:33]
	v_lshl_add_u64 v[32:33], v[32:33], 2, s[2:3]
	global_load_dword v51, v[32:33], off sc1 nt
	v_or_b32_e32 v32, 18, v16
	v_lshl_add_u64 v[34:35], v[14:15], 0, v[34:35]
	v_ashrrev_i32_e32 v33, 31, v32
	global_load_dword v50, v[34:35], off sc1 nt
	v_lshlrev_b64 v[34:35], 14, v[32:33]
	v_lshl_add_u64 v[32:33], v[32:33], 2, s[2:3]
	global_load_dword v53, v[32:33], off sc1 nt
	v_or_b32_e32 v32, 20, v16
	v_lshl_add_u64 v[34:35], v[14:15], 0, v[34:35]
	v_ashrrev_i32_e32 v33, 31, v32
	global_load_dword v52, v[34:35], off sc1 nt
	v_lshlrev_b64 v[34:35], 14, v[32:33]
	v_lshl_add_u64 v[32:33], v[32:33], 2, s[2:3]
	global_load_dword v55, v[32:33], off sc1 nt
	v_or_b32_e32 v32, 22, v16
	v_lshl_add_u64 v[34:35], v[14:15], 0, v[34:35]
	v_ashrrev_i32_e32 v33, 31, v32
	global_load_dword v54, v[34:35], off sc1 nt
	v_lshlrev_b64 v[34:35], 14, v[32:33]
	v_lshl_add_u64 v[32:33], v[32:33], 2, s[2:3]
	global_load_dword v57, v[32:33], off sc1 nt
	v_or_b32_e32 v32, 24, v16
	v_lshl_add_u64 v[34:35], v[14:15], 0, v[34:35]
	v_ashrrev_i32_e32 v33, 31, v32
	global_load_dword v56, v[34:35], off sc1 nt
	v_lshlrev_b64 v[34:35], 14, v[32:33]
	v_lshl_add_u64 v[32:33], v[32:33], 2, s[2:3]
	global_load_dword v59, v[32:33], off sc1 nt
	v_or_b32_e32 v32, 26, v16
	v_lshl_add_u64 v[34:35], v[14:15], 0, v[34:35]
	v_ashrrev_i32_e32 v33, 31, v32
	global_load_dword v58, v[34:35], off sc1 nt
	v_lshlrev_b64 v[34:35], 14, v[32:33]
	v_lshl_add_u64 v[32:33], v[32:33], 2, s[2:3]
	global_load_dword v61, v[32:33], off sc1 nt
	v_or_b32_e32 v32, 28, v16
	v_lshl_add_u64 v[34:35], v[14:15], 0, v[34:35]
	v_ashrrev_i32_e32 v33, 31, v32
	global_load_dword v60, v[34:35], off sc1 nt
	v_lshlrev_b64 v[34:35], 14, v[32:33]
	v_lshl_add_u64 v[32:33], v[32:33], 2, s[2:3]
	global_load_dword v63, v[32:33], off sc1 nt
	v_or_b32_e32 v32, 30, v16
	v_lshl_add_u64 v[34:35], v[14:15], 0, v[34:35]
	v_ashrrev_i32_e32 v33, 31, v32
	global_load_dword v62, v[34:35], off sc1 nt
	v_lshlrev_b64 v[34:35], 14, v[32:33]
	v_lshl_add_u64 v[32:33], v[32:33], 2, s[2:3]
	global_load_dword v65, v[32:33], off sc1 nt
	v_or_b32_e32 v32, 32, v16
	v_lshl_add_u64 v[34:35], v[14:15], 0, v[34:35]
	v_ashrrev_i32_e32 v33, 31, v32
	global_load_dword v64, v[34:35], off sc1 nt
	v_lshlrev_b64 v[34:35], 14, v[32:33]
	v_lshl_add_u64 v[32:33], v[32:33], 2, s[2:3]
	global_load_dword v67, v[32:33], off sc1 nt
	v_or_b32_e32 v32, 34, v16
	v_lshl_add_u64 v[34:35], v[14:15], 0, v[34:35]
	v_ashrrev_i32_e32 v33, 31, v32
	global_load_dword v66, v[34:35], off sc1 nt
	v_lshlrev_b64 v[34:35], 14, v[32:33]
	v_lshl_add_u64 v[32:33], v[32:33], 2, s[2:3]
	global_load_dword v69, v[32:33], off sc1 nt
	v_or_b32_e32 v32, 36, v16
	v_lshl_add_u64 v[34:35], v[14:15], 0, v[34:35]
	v_ashrrev_i32_e32 v33, 31, v32
	global_load_dword v68, v[34:35], off sc1 nt
	v_lshlrev_b64 v[34:35], 14, v[32:33]
	v_lshl_add_u64 v[32:33], v[32:33], 2, s[2:3]
	global_load_dword v71, v[32:33], off sc1 nt
	v_or_b32_e32 v32, 38, v16
	v_lshl_add_u64 v[34:35], v[14:15], 0, v[34:35]
	v_ashrrev_i32_e32 v33, 31, v32
	global_load_dword v70, v[34:35], off sc1 nt
	v_lshlrev_b64 v[34:35], 14, v[32:33]
	v_lshl_add_u64 v[32:33], v[32:33], 2, s[2:3]
	global_load_dword v73, v[32:33], off sc1 nt
	v_or_b32_e32 v32, 40, v16
	v_lshl_add_u64 v[34:35], v[14:15], 0, v[34:35]
	v_ashrrev_i32_e32 v33, 31, v32
	global_load_dword v72, v[34:35], off sc1 nt
	v_lshlrev_b64 v[34:35], 14, v[32:33]
	v_lshl_add_u64 v[32:33], v[32:33], 2, s[2:3]
	global_load_dword v75, v[32:33], off sc1 nt
	v_or_b32_e32 v32, 42, v16
	v_lshl_add_u64 v[34:35], v[14:15], 0, v[34:35]
	v_ashrrev_i32_e32 v33, 31, v32
	global_load_dword v74, v[34:35], off sc1 nt
	v_lshlrev_b64 v[34:35], 14, v[32:33]
	v_lshl_add_u64 v[32:33], v[32:33], 2, s[2:3]
	global_load_dword v77, v[32:33], off sc1 nt
	v_or_b32_e32 v32, 44, v16
	v_lshl_add_u64 v[34:35], v[14:15], 0, v[34:35]
	v_ashrrev_i32_e32 v33, 31, v32
	global_load_dword v76, v[34:35], off sc1 nt
	v_lshlrev_b64 v[34:35], 14, v[32:33]
	v_lshl_add_u64 v[32:33], v[32:33], 2, s[2:3]
	global_load_dword v79, v[32:33], off sc1 nt
	v_or_b32_e32 v32, 46, v16
	v_lshl_add_u64 v[34:35], v[14:15], 0, v[34:35]
	v_ashrrev_i32_e32 v33, 31, v32
	global_load_dword v78, v[34:35], off sc1 nt
	v_lshlrev_b64 v[34:35], 14, v[32:33]
	v_lshl_add_u64 v[32:33], v[32:33], 2, s[2:3]
	global_load_dword v81, v[32:33], off sc1 nt
	v_or_b32_e32 v32, 48, v16
	v_lshl_add_u64 v[34:35], v[14:15], 0, v[34:35]
	v_ashrrev_i32_e32 v33, 31, v32
	global_load_dword v80, v[34:35], off sc1 nt
	v_lshlrev_b64 v[34:35], 14, v[32:33]
	v_lshl_add_u64 v[32:33], v[32:33], 2, s[2:3]
	global_load_dword v83, v[32:33], off sc1 nt
	v_or_b32_e32 v32, 50, v16
	v_lshl_add_u64 v[34:35], v[14:15], 0, v[34:35]
	v_ashrrev_i32_e32 v33, 31, v32
	global_load_dword v82, v[34:35], off sc1 nt
	v_lshlrev_b64 v[34:35], 14, v[32:33]
	v_lshl_add_u64 v[32:33], v[32:33], 2, s[2:3]
	global_load_dword v85, v[32:33], off sc1 nt
	v_or_b32_e32 v32, 52, v16
	v_lshl_add_u64 v[34:35], v[14:15], 0, v[34:35]
	v_ashrrev_i32_e32 v33, 31, v32
	global_load_dword v84, v[34:35], off sc1 nt
	v_lshlrev_b64 v[34:35], 14, v[32:33]
	v_lshl_add_u64 v[32:33], v[32:33], 2, s[2:3]
	global_load_dword v87, v[32:33], off sc1 nt
	v_or_b32_e32 v32, 54, v16
	v_lshl_add_u64 v[34:35], v[14:15], 0, v[34:35]
	v_ashrrev_i32_e32 v33, 31, v32
	global_load_dword v86, v[34:35], off sc1 nt
	v_lshlrev_b64 v[34:35], 14, v[32:33]
	v_lshl_add_u64 v[32:33], v[32:33], 2, s[2:3]
	global_load_dword v89, v[32:33], off sc1 nt
	v_or_b32_e32 v32, 56, v16
	v_lshl_add_u64 v[34:35], v[14:15], 0, v[34:35]
	v_ashrrev_i32_e32 v33, 31, v32
	global_load_dword v88, v[34:35], off sc1 nt
	v_lshlrev_b64 v[34:35], 14, v[32:33]
	v_lshl_add_u64 v[32:33], v[32:33], 2, s[2:3]
	global_load_dword v91, v[32:33], off sc1 nt
	v_or_b32_e32 v32, 58, v16
	v_lshl_add_u64 v[34:35], v[14:15], 0, v[34:35]
	v_ashrrev_i32_e32 v33, 31, v32
	global_load_dword v90, v[34:35], off sc1 nt
	v_lshlrev_b64 v[34:35], 14, v[32:33]
	v_lshl_add_u64 v[32:33], v[32:33], 2, s[2:3]
	global_load_dword v93, v[32:33], off sc1 nt
	v_or_b32_e32 v32, 60, v16
	v_lshl_add_u64 v[34:35], v[14:15], 0, v[34:35]
	v_ashrrev_i32_e32 v33, 31, v32
	global_load_dword v92, v[34:35], off sc1 nt
	v_lshlrev_b64 v[34:35], 14, v[32:33]
	v_or_b32_e32 v16, 62, v16
	v_lshl_add_u64 v[34:35], v[14:15], 0, v[34:35]
	v_lshl_add_u64 v[32:33], v[32:33], 2, s[2:3]
	v_ashrrev_i32_e32 v17, 31, v16
	global_load_dword v34, v[34:35], off sc1 nt
	s_waitcnt vmcnt(59)
	v_mul_f32_e32 v0, v0, v31
	global_load_dword v35, v[32:33], off sc1 nt
	v_lshlrev_b64 v[32:33], 14, v[16:17]
	v_lshl_add_u64 v[14:15], v[14:15], 0, v[32:33]
	global_load_dword v32, v[14:15], off sc1 nt
	v_lshl_add_u64 v[14:15], v[16:17], 2, s[2:3]
	global_load_dword v14, v[14:15], off sc1 nt
	s_waitcnt vmcnt(60)
	v_mul_f32_e32 v15, v36, v37
	ds_write2_b32 v18, v0, v15 offset1:66
	s_waitcnt vmcnt(58)
	v_mul_f32_e32 v0, v38, v39
	s_waitcnt vmcnt(56)
	v_mul_f32_e32 v15, v40, v41
	ds_write2_b32 v18, v0, v15 offset0:132 offset1:198
	s_waitcnt vmcnt(54)
	v_mul_f32_e32 v0, v42, v43
	s_waitcnt vmcnt(52)
	v_mul_f32_e32 v15, v44, v45
	ds_write2_b32 v24, v0, v15 offset0:8 offset1:74
	s_waitcnt vmcnt(50)
	v_mul_f32_e32 v0, v46, v47
	s_waitcnt vmcnt(48)
	v_mul_f32_e32 v15, v48, v49
	ds_write2_b32 v24, v0, v15 offset0:140 offset1:206
	s_waitcnt vmcnt(46)
	v_mul_f32_e32 v0, v50, v51
	s_waitcnt vmcnt(44)
	v_mul_f32_e32 v15, v52, v53
	ds_write2_b32 v25, v0, v15 offset0:16 offset1:82
	s_waitcnt vmcnt(42)
	v_mul_f32_e32 v0, v54, v55
	s_waitcnt vmcnt(40)
	v_mul_f32_e32 v15, v56, v57
	ds_write2_b32 v25, v0, v15 offset0:148 offset1:214
	s_waitcnt vmcnt(38)
	v_mul_f32_e32 v0, v58, v59
	s_waitcnt vmcnt(36)
	v_mul_f32_e32 v15, v60, v61
	ds_write2_b32 v26, v0, v15 offset0:24 offset1:90
	s_waitcnt vmcnt(34)
	v_mul_f32_e32 v0, v62, v63
	s_waitcnt vmcnt(32)
	v_mul_f32_e32 v15, v64, v65
	ds_write2_b32 v26, v0, v15 offset0:156 offset1:222
	s_waitcnt vmcnt(30)
	v_mul_f32_e32 v0, v66, v67
	s_waitcnt vmcnt(28)
	v_mul_f32_e32 v15, v68, v69
	ds_write2_b32 v27, v0, v15 offset0:32 offset1:98
	s_waitcnt vmcnt(26)
	v_mul_f32_e32 v0, v70, v71
	s_waitcnt vmcnt(24)
	v_mul_f32_e32 v15, v72, v73
	ds_write2_b32 v27, v0, v15 offset0:164 offset1:230
	s_waitcnt vmcnt(22)
	v_mul_f32_e32 v0, v74, v75
	s_waitcnt vmcnt(20)
	v_mul_f32_e32 v15, v76, v77
	ds_write2_b32 v28, v0, v15 offset0:40 offset1:106
	s_waitcnt vmcnt(18)
	v_mul_f32_e32 v0, v78, v79
	s_waitcnt vmcnt(16)
	v_mul_f32_e32 v15, v80, v81
	ds_write2_b32 v28, v0, v15 offset0:172 offset1:238
	s_waitcnt vmcnt(14)
	v_mul_f32_e32 v0, v82, v83
	v_add_u32_e32 v50, s4, v19
	s_ashr_i32 s7, s6, 31
	s_waitcnt vmcnt(12)
	v_mul_f32_e32 v15, v84, v85
	ds_write2_b32 v29, v0, v15 offset0:48 offset1:114
	v_ashrrev_i32_e32 v51, 31, v50
	v_lshl_add_u64 v[48:49], s[6:7], 1, v[12:13]
	v_lshlrev_b64 v[52:53], 11, v[50:51]
	v_lshl_add_u64 v[52:53], v[48:49], 0, v[52:53]
	s_waitcnt vmcnt(10)
	v_mul_f32_e32 v0, v86, v87
	s_waitcnt vmcnt(8)
	v_mul_f32_e32 v15, v88, v89
	ds_write2_b32 v29, v0, v15 offset0:180 offset1:246
	s_waitcnt vmcnt(6)
	v_mul_f32_e32 v0, v90, v91
	s_waitcnt vmcnt(4)
	v_mul_f32_e32 v15, v92, v93
	ds_write2_b32 v30, v0, v15 offset0:56 offset1:122
	s_waitcnt vmcnt(2)
	v_mul_f32_e32 v0, v34, v35
	s_waitcnt vmcnt(0)
	v_mul_f32_e32 v14, v32, v14
	ds_write2_b32 v30, v0, v14 offset0:188 offset1:254
	s_waitcnt lgkmcnt(0)
	ds_read2_b32 v[32:33], v20 offset0:33 offset1:41
	ds_read2_b32 v[34:35], v20 offset1:8
	ds_read2_b32 v[36:37], v20 offset0:66 offset1:74
	ds_read2_b32 v[38:39], v20 offset0:99 offset1:107
	ds_read2_b32 v[40:41], v20 offset0:132 offset1:140
	ds_read2_b32 v[42:43], v20 offset0:165 offset1:173
	ds_read2_b32 v[44:45], v20 offset0:198 offset1:206
	ds_read2_b32 v[46:47], v20 offset0:231 offset1:239
	s_waitcnt lgkmcnt(6)
	v_cvt_pk_bf16_f32 v14, v34, v32
	s_waitcnt lgkmcnt(4)
	v_cvt_pk_bf16_f32 v15, v36, v38
	s_waitcnt lgkmcnt(2)
	v_cvt_pk_bf16_f32 v16, v40, v42
	v_add_u32_e32 v32, 8, v50
	s_waitcnt lgkmcnt(0)
	v_cvt_pk_bf16_f32 v17, v44, v46
	global_store_dwordx4 v[52:53], v[14:17], off
	s_nop 1
	v_cvt_pk_bf16_f32 v14, v35, v33
	v_ashrrev_i32_e32 v33, 31, v32
	v_cvt_pk_bf16_f32 v15, v37, v39
	v_cvt_pk_bf16_f32 v16, v41, v43
	v_cvt_pk_bf16_f32 v17, v45, v47
	v_lshlrev_b64 v[32:33], 11, v[32:33]
	ds_read2_b32 v[34:35], v20 offset0:49 offset1:57
	ds_read2_b32 v[36:37], v20 offset0:16 offset1:24
	ds_read2_b32 v[38:39], v20 offset0:82 offset1:90
	ds_read2_b32 v[40:41], v20 offset0:115 offset1:123
	ds_read2_b32 v[42:43], v20 offset0:148 offset1:156
	ds_read2_b32 v[44:45], v20 offset0:181 offset1:189
	ds_read2_b32 v[46:47], v20 offset0:214 offset1:222
	ds_read2_b32 v[52:53], v20 offset0:247 offset1:255
	v_lshl_add_u64 v[32:33], v[48:49], 0, v[32:33]
	global_store_dwordx4 v[32:33], v[14:17], off
	v_add_u32_e32 v32, 16, v50
	v_ashrrev_i32_e32 v33, 31, v32
	v_lshlrev_b64 v[32:33], 11, v[32:33]
	s_waitcnt lgkmcnt(6)
	v_cvt_pk_bf16_f32 v14, v36, v34
	s_waitcnt lgkmcnt(4)
	v_cvt_pk_bf16_f32 v15, v38, v40
	s_waitcnt lgkmcnt(2)
	v_cvt_pk_bf16_f32 v16, v42, v44
	s_waitcnt lgkmcnt(0)
	v_cvt_pk_bf16_f32 v17, v46, v52
	v_lshl_add_u64 v[32:33], v[48:49], 0, v[32:33]
	global_store_dwordx4 v[32:33], v[14:17], off
	v_add_u32_e32 v32, 24, v50
	v_ashrrev_i32_e32 v33, 31, v32
	v_lshlrev_b64 v[32:33], 11, v[32:33]
	v_cvt_pk_bf16_f32 v14, v37, v35
	v_cvt_pk_bf16_f32 v15, v39, v41
	v_cvt_pk_bf16_f32 v16, v43, v45
	v_cvt_pk_bf16_f32 v17, v47, v53
	v_lshl_add_u64 v[32:33], v[48:49], 0, v[32:33]
	global_store_dwordx4 v[32:33], v[14:17], off
	s_waitcnt lgkmcnt(0)
	s_branch .LBB0_835

.LBB0_849:
	s_cmpk_gt_i32 s8, 0x7ff
	s_mov_b64 s[4:5], -1
	s_cbranch_scc0 .LBB0_855
	s_and_b32 s6, s9, 0x3e0
	s_cmpk_gt_u32 s8, 0x9ff
	v_or_b32_e32 v17, s6, v19
	v_or_b32_e32 v16, s6, v21
	v_or_b32_e32 v15, s6, v22
	v_or_b32_e32 v14, s6, v23
	s_cbranch_scc0 .LBB0_852
	s_and_b32 s4, s10, 0x1ffc0
	v_or_b32_e32 v0, s4, v229
	s_lshl_b32 s0, s6, 2
	v_lshl_add_u64 v[32:33], v[4:5], 0, s[0:1]
	v_lshlrev_b32_e32 v0, 12, v0
	v_lshl_add_u64 v[32:33], v[32:33], 0, v[0:1]
	v_add_co_u32_e32 v34, vcc, 0x2000, v32
	s_lshl_b32 s0, s4, 1
	s_nop 0
	v_addc_co_u32_e32 v35, vcc, 0, v33, vcc
	v_add_co_u32_e32 v36, vcc, 0x4000, v32
	s_mov_b64 s[4:5], 0
	s_nop 0
	v_addc_co_u32_e32 v37, vcc, 0, v33, vcc
	v_add_co_u32_e32 v38, vcc, 0x6000, v32
	s_nop 1
	v_addc_co_u32_e32 v39, vcc, 0, v33, vcc
	v_add_co_u32_e32 v40, vcc, 0x8000, v32
	s_nop 1
	v_addc_co_u32_e32 v41, vcc, 0, v33, vcc
	v_add_co_u32_e32 v42, vcc, 0xa000, v32
	s_nop 1
	v_addc_co_u32_e32 v43, vcc, 0, v33, vcc
	v_add_co_u32_e32 v44, vcc, 0xc000, v32
	s_nop 1
	v_addc_co_u32_e32 v45, vcc, 0, v33, vcc
	v_add_co_u32_e32 v46, vcc, 0xe000, v32
	s_nop 1
	v_addc_co_u32_e32 v47, vcc, 0, v33, vcc
	global_load_dword v0, v[32:33], off sc1 nt
	global_load_dword v31, v[34:35], off sc1 nt
	global_load_dword v50, v[36:37], off sc1 nt
	global_load_dword v51, v[38:39], off sc1 nt
	global_load_dword v52, v[40:41], off sc1 nt
	global_load_dword v53, v[42:43], off sc1 nt
	global_load_dword v54, v[44:45], off sc1 nt
	global_load_dword v55, v[46:47], off sc1 nt
	v_add_co_u32_e32 v34, vcc, 0x10000, v32
	s_nop 1
	v_addc_co_u32_e32 v35, vcc, 0, v33, vcc
	v_add_co_u32_e32 v36, vcc, 0x12000, v32
	s_nop 1
	v_addc_co_u32_e32 v37, vcc, 0, v33, vcc
	v_add_co_u32_e32 v38, vcc, 0x14000, v32
	s_nop 1
	v_addc_co_u32_e32 v39, vcc, 0, v33, vcc
	v_add_co_u32_e32 v40, vcc, 0x16000, v32
	s_nop 1
	v_addc_co_u32_e32 v41, vcc, 0, v33, vcc
	v_add_co_u32_e32 v42, vcc, 0x18000, v32
	s_nop 1
	v_addc_co_u32_e32 v43, vcc, 0, v33, vcc
	v_add_co_u32_e32 v44, vcc, 0x1a000, v32
	s_nop 1
	v_addc_co_u32_e32 v45, vcc, 0, v33, vcc
	v_add_co_u32_e32 v46, vcc, 0x1c000, v32
	s_nop 1
	v_addc_co_u32_e32 v47, vcc, 0, v33, vcc
	v_add_co_u32_e32 v48, vcc, 0x1e000, v32
	s_nop 1
	v_addc_co_u32_e32 v49, vcc, 0, v33, vcc
	global_load_dword v56, v[34:35], off sc1 nt
	global_load_dword v57, v[36:37], off sc1 nt
	global_load_dword v58, v[38:39], off sc1 nt
	global_load_dword v59, v[40:41], off sc1 nt
	global_load_dword v60, v[42:43], off sc1 nt
	global_load_dword v61, v[44:45], off sc1 nt
	global_load_dword v62, v[46:47], off sc1 nt
	global_load_dword v63, v[48:49], off sc1 nt
	v_add_co_u32_e32 v34, vcc, 0x20000, v32
	s_nop 1
	v_addc_co_u32_e32 v35, vcc, 0, v33, vcc
	v_add_co_u32_e32 v36, vcc, 0x22000, v32
	s_nop 1
	v_addc_co_u32_e32 v37, vcc, 0, v33, vcc
	v_add_co_u32_e32 v38, vcc, 0x24000, v32
	s_nop 1
	v_addc_co_u32_e32 v39, vcc, 0, v33, vcc
	v_add_co_u32_e32 v40, vcc, 0x26000, v32
	s_nop 1
	v_addc_co_u32_e32 v41, vcc, 0, v33, vcc
	v_add_co_u32_e32 v42, vcc, 0x28000, v32
	s_nop 1
	v_addc_co_u32_e32 v43, vcc, 0, v33, vcc
	v_add_co_u32_e32 v44, vcc, 0x2a000, v32
	s_nop 1
	v_addc_co_u32_e32 v45, vcc, 0, v33, vcc
	v_add_co_u32_e32 v46, vcc, 0x2c000, v32
	s_nop 1
	v_addc_co_u32_e32 v47, vcc, 0, v33, vcc
	v_add_co_u32_e32 v48, vcc, 0x2e000, v32
	s_nop 1
	v_addc_co_u32_e32 v49, vcc, 0, v33, vcc
	global_load_dword v64, v[34:35], off sc1 nt
	global_load_dword v65, v[36:37], off sc1 nt
	global_load_dword v66, v[38:39], off sc1 nt
	global_load_dword v67, v[40:41], off sc1 nt
	global_load_dword v68, v[42:43], off sc1 nt
	global_load_dword v69, v[44:45], off sc1 nt
	global_load_dword v70, v[46:47], off sc1 nt
	global_load_dword v71, v[48:49], off sc1 nt
	v_add_co_u32_e32 v34, vcc, 0x30000, v32
	s_nop 1
	v_addc_co_u32_e32 v35, vcc, 0, v33, vcc
	v_add_co_u32_e32 v36, vcc, 0x32000, v32
	s_nop 1
	v_addc_co_u32_e32 v37, vcc, 0, v33, vcc
	v_add_co_u32_e32 v38, vcc, 0x34000, v32
	s_nop 1
	v_addc_co_u32_e32 v39, vcc, 0, v33, vcc
	v_add_co_u32_e32 v40, vcc, 0x36000, v32
	s_nop 1
	v_addc_co_u32_e32 v41, vcc, 0, v33, vcc
	v_add_co_u32_e32 v42, vcc, 0x38000, v32
	s_nop 1
	v_addc_co_u32_e32 v43, vcc, 0, v33, vcc
	v_add_co_u32_e32 v44, vcc, 0x3a000, v32
	s_nop 1
	v_addc_co_u32_e32 v45, vcc, 0, v33, vcc
	v_add_co_u32_e32 v46, vcc, 0x3c000, v32
	s_nop 1
	v_addc_co_u32_e32 v47, vcc, 0, v33, vcc
	v_add_co_u32_e32 v32, vcc, 0x3e000, v32
	s_nop 1
	v_addc_co_u32_e32 v33, vcc, 0, v33, vcc
	global_load_dword v48, v[34:35], off sc1 nt
	global_load_dword v49, v[36:37], off sc1 nt
	global_load_dword v72, v[38:39], off sc1 nt
	global_load_dword v73, v[40:41], off sc1 nt
	global_load_dword v74, v[42:43], off sc1 nt
	global_load_dword v75, v[44:45], off sc1 nt
	global_load_dword v76, v[46:47], off sc1 nt
	global_load_dword v77, v[32:33], off sc1 nt
	s_waitcnt vmcnt(30)
	ds_write2_b32 v18, v0, v31 offset1:66
	s_waitcnt vmcnt(28)
	ds_write2_b32 v18, v50, v51 offset0:132 offset1:198
	s_waitcnt vmcnt(26)
	ds_write2_b32 v24, v52, v53 offset0:8 offset1:74
	s_waitcnt vmcnt(24)
	ds_write2_b32 v24, v54, v55 offset0:140 offset1:206
	s_waitcnt vmcnt(22)
	ds_write2_b32 v25, v56, v57 offset0:16 offset1:82
	s_waitcnt vmcnt(20)
	ds_write2_b32 v25, v58, v59 offset0:148 offset1:214
	s_waitcnt vmcnt(18)
	ds_write2_b32 v26, v60, v61 offset0:24 offset1:90
	s_waitcnt vmcnt(16)
	ds_write2_b32 v26, v62, v63 offset0:156 offset1:222
	s_waitcnt vmcnt(14)
	ds_write2_b32 v27, v64, v65 offset0:32 offset1:98
	s_waitcnt vmcnt(12)
	ds_write2_b32 v27, v66, v67 offset0:164 offset1:230
	s_waitcnt vmcnt(10)
	ds_write2_b32 v28, v68, v69 offset0:40 offset1:106
	s_waitcnt vmcnt(8)
	ds_write2_b32 v28, v70, v71 offset0:172 offset1:238
	s_waitcnt vmcnt(6)
	ds_write2_b32 v29, v48, v49 offset0:48 offset1:114
	s_waitcnt vmcnt(4)
	ds_write2_b32 v29, v72, v73 offset0:180 offset1:246
	s_waitcnt vmcnt(2)
	ds_write2_b32 v30, v74, v75 offset0:56 offset1:122
	s_waitcnt vmcnt(0)
	ds_write2_b32 v30, v76, v77 offset0:188 offset1:254
	s_waitcnt lgkmcnt(0)
	ds_read2_b32 v[36:37], v20 offset0:33 offset1:41
	ds_read2_b32 v[38:39], v20 offset1:8
	ds_read2_b32 v[40:41], v20 offset0:66 offset1:74
	ds_read2_b32 v[42:43], v20 offset0:99 offset1:107
	ds_read2_b32 v[44:45], v20 offset0:132 offset1:140
	ds_read2_b32 v[46:47], v20 offset0:165 offset1:173
	ds_read2_b32 v[48:49], v20 offset0:198 offset1:206
	ds_read2_b32 v[50:51], v20 offset0:231 offset1:239
	v_lshl_add_u64 v[52:53], v[6:7], 0, s[0:1]
	v_lshlrev_b32_e32 v0, 13, v17
	s_waitcnt lgkmcnt(6)
	v_cvt_pk_bf16_f32 v32, v38, v36
	s_waitcnt lgkmcnt(4)
	v_cvt_pk_bf16_f32 v33, v40, v42
	s_waitcnt lgkmcnt(2)
	v_cvt_pk_bf16_f32 v34, v44, v46
	s_waitcnt lgkmcnt(0)
	v_cvt_pk_bf16_f32 v35, v48, v50
	v_lshl_add_u64 v[54:55], v[52:53], 0, v[0:1]
	global_store_dwordx4 v[54:55], v[32:35], off
	v_lshlrev_b32_e32 v0, 13, v16
	s_nop 0
	v_cvt_pk_bf16_f32 v32, v39, v37
	v_cvt_pk_bf16_f32 v33, v41, v43
	v_cvt_pk_bf16_f32 v34, v45, v47
	v_cvt_pk_bf16_f32 v35, v49, v51
	ds_read2_b32 v[38:39], v20 offset0:49 offset1:57
	ds_read2_b32 v[40:41], v20 offset0:16 offset1:24
	ds_read2_b32 v[42:43], v20 offset0:82 offset1:90
	ds_read2_b32 v[44:45], v20 offset0:115 offset1:123
	ds_read2_b32 v[46:47], v20 offset0:148 offset1:156
	ds_read2_b32 v[48:49], v20 offset0:181 offset1:189
	ds_read2_b32 v[50:51], v20 offset0:214 offset1:222
	ds_read2_b32 v[54:55], v20 offset0:247 offset1:255
	v_lshl_add_u64 v[36:37], v[52:53], 0, v[0:1]
	v_lshlrev_b32_e32 v0, 13, v15
	global_store_dwordx4 v[36:37], v[32:35], off
	v_lshl_add_u64 v[36:37], v[52:53], 0, v[0:1]
	v_lshlrev_b32_e32 v0, 13, v14
	s_waitcnt lgkmcnt(6)
	v_cvt_pk_bf16_f32 v32, v40, v38
	s_waitcnt lgkmcnt(4)
	v_cvt_pk_bf16_f32 v33, v42, v44
	s_waitcnt lgkmcnt(2)
	v_cvt_pk_bf16_f32 v34, v46, v48
	s_waitcnt lgkmcnt(0)
	v_cvt_pk_bf16_f32 v35, v50, v54
	global_store_dwordx4 v[36:37], v[32:35], off
	v_lshl_add_u64 v[36:37], v[52:53], 0, v[0:1]
	s_nop 0
	v_cvt_pk_bf16_f32 v32, v41, v39
	v_cvt_pk_bf16_f32 v33, v43, v45
	v_cvt_pk_bf16_f32 v34, v47, v49
	v_cvt_pk_bf16_f32 v35, v51, v55
	global_store_dwordx4 v[36:37], v[32:35], off
	s_waitcnt lgkmcnt(0)
.LBB0_852:
	s_andn2_b64 vcc, exec, s[4:5]
	s_cbranch_vccnz .LBB0_854
	s_add_i32 s0, s10, 0x400
	s_and_b32 s4, s0, 0x1ffc0
	v_or_b32_e32 v0, s4, v229
	s_lshl_b32 s0, s6, 2
	v_lshl_add_u64 v[32:33], v[2:3], 0, s[0:1]
	v_lshlrev_b32_e32 v0, 12, v0
	v_lshl_add_u64 v[32:33], v[32:33], 0, v[0:1]
	v_add_co_u32_e32 v34, vcc, 0x2000, v32
	s_lshl_b32 s0, s4, 1
	s_nop 0
	v_addc_co_u32_e32 v35, vcc, 0, v33, vcc
	v_add_co_u32_e32 v36, vcc, 0x4000, v32
	s_nop 1
	v_addc_co_u32_e32 v37, vcc, 0, v33, vcc
	v_add_co_u32_e32 v38, vcc, 0x6000, v32
	s_nop 1
	v_addc_co_u32_e32 v39, vcc, 0, v33, vcc
	v_add_co_u32_e32 v40, vcc, 0x8000, v32
	s_nop 1
	v_addc_co_u32_e32 v41, vcc, 0, v33, vcc
	v_add_co_u32_e32 v42, vcc, 0xa000, v32
	s_nop 1
	v_addc_co_u32_e32 v43, vcc, 0, v33, vcc
	v_add_co_u32_e32 v44, vcc, 0xc000, v32
	s_nop 1
	v_addc_co_u32_e32 v45, vcc, 0, v33, vcc
	v_add_co_u32_e32 v46, vcc, 0xe000, v32
	s_nop 1
	v_addc_co_u32_e32 v47, vcc, 0, v33, vcc
	global_load_dword v0, v[32:33], off sc1 nt
	global_load_dword v31, v[34:35], off sc1 nt
	global_load_dword v50, v[36:37], off sc1 nt
	global_load_dword v51, v[38:39], off sc1 nt
	global_load_dword v52, v[40:41], off sc1 nt
	global_load_dword v53, v[42:43], off sc1 nt
	global_load_dword v54, v[44:45], off sc1 nt
	global_load_dword v55, v[46:47], off sc1 nt
	v_add_co_u32_e32 v34, vcc, 0x10000, v32
	s_nop 1
	v_addc_co_u32_e32 v35, vcc, 0, v33, vcc
	v_add_co_u32_e32 v36, vcc, 0x12000, v32
	s_nop 1
	v_addc_co_u32_e32 v37, vcc, 0, v33, vcc
	v_add_co_u32_e32 v38, vcc, 0x14000, v32
	s_nop 1
	v_addc_co_u32_e32 v39, vcc, 0, v33, vcc
	v_add_co_u32_e32 v40, vcc, 0x16000, v32
	s_nop 1
	v_addc_co_u32_e32 v41, vcc, 0, v33, vcc
	v_add_co_u32_e32 v42, vcc, 0x18000, v32
	s_nop 1
	v_addc_co_u32_e32 v43, vcc, 0, v33, vcc
	v_add_co_u32_e32 v44, vcc, 0x1a000, v32
	s_nop 1
	v_addc_co_u32_e32 v45, vcc, 0, v33, vcc
	v_add_co_u32_e32 v46, vcc, 0x1c000, v32
	s_nop 1
	v_addc_co_u32_e32 v47, vcc, 0, v33, vcc
	v_add_co_u32_e32 v48, vcc, 0x1e000, v32
	s_nop 1
	v_addc_co_u32_e32 v49, vcc, 0, v33, vcc
	global_load_dword v56, v[34:35], off sc1 nt
	global_load_dword v57, v[36:37], off sc1 nt
	global_load_dword v58, v[38:39], off sc1 nt
	global_load_dword v59, v[40:41], off sc1 nt
	global_load_dword v60, v[42:43], off sc1 nt
	global_load_dword v61, v[44:45], off sc1 nt
	global_load_dword v62, v[46:47], off sc1 nt
	global_load_dword v63, v[48:49], off sc1 nt
	v_add_co_u32_e32 v34, vcc, 0x20000, v32
	s_nop 1
	v_addc_co_u32_e32 v35, vcc, 0, v33, vcc
	v_add_co_u32_e32 v36, vcc, 0x22000, v32
	s_nop 1
	v_addc_co_u32_e32 v37, vcc, 0, v33, vcc
	v_add_co_u32_e32 v38, vcc, 0x24000, v32
	s_nop 1
	v_addc_co_u32_e32 v39, vcc, 0, v33, vcc
	v_add_co_u32_e32 v40, vcc, 0x26000, v32
	s_nop 1
	v_addc_co_u32_e32 v41, vcc, 0, v33, vcc
	v_add_co_u32_e32 v42, vcc, 0x28000, v32
	s_nop 1
	v_addc_co_u32_e32 v43, vcc, 0, v33, vcc
	v_add_co_u32_e32 v44, vcc, 0x2a000, v32
	s_nop 1
	v_addc_co_u32_e32 v45, vcc, 0, v33, vcc
	v_add_co_u32_e32 v46, vcc, 0x2c000, v32
	s_nop 1
	v_addc_co_u32_e32 v47, vcc, 0, v33, vcc
	v_add_co_u32_e32 v48, vcc, 0x2e000, v32
	s_nop 1
	v_addc_co_u32_e32 v49, vcc, 0, v33, vcc
	global_load_dword v64, v[34:35], off sc1 nt
	global_load_dword v65, v[36:37], off sc1 nt
	global_load_dword v66, v[38:39], off sc1 nt
	global_load_dword v67, v[40:41], off sc1 nt
	global_load_dword v68, v[42:43], off sc1 nt
	global_load_dword v69, v[44:45], off sc1 nt
	global_load_dword v70, v[46:47], off sc1 nt
	global_load_dword v71, v[48:49], off sc1 nt
	v_add_co_u32_e32 v34, vcc, 0x30000, v32
	s_nop 1
	v_addc_co_u32_e32 v35, vcc, 0, v33, vcc
	v_add_co_u32_e32 v36, vcc, 0x32000, v32
	s_nop 1
	v_addc_co_u32_e32 v37, vcc, 0, v33, vcc
	v_add_co_u32_e32 v38, vcc, 0x34000, v32
	s_nop 1
	v_addc_co_u32_e32 v39, vcc, 0, v33, vcc
	v_add_co_u32_e32 v40, vcc, 0x36000, v32
	s_nop 1
	v_addc_co_u32_e32 v41, vcc, 0, v33, vcc
	v_add_co_u32_e32 v42, vcc, 0x38000, v32
	s_nop 1
	v_addc_co_u32_e32 v43, vcc, 0, v33, vcc
	v_add_co_u32_e32 v44, vcc, 0x3a000, v32
	s_nop 1
	v_addc_co_u32_e32 v45, vcc, 0, v33, vcc
	v_add_co_u32_e32 v46, vcc, 0x3c000, v32
	s_nop 1
	v_addc_co_u32_e32 v47, vcc, 0, v33, vcc
	v_add_co_u32_e32 v32, vcc, 0x3e000, v32
	s_nop 1
	v_addc_co_u32_e32 v33, vcc, 0, v33, vcc
	global_load_dword v48, v[34:35], off sc1 nt
	global_load_dword v49, v[36:37], off sc1 nt
	global_load_dword v72, v[38:39], off sc1 nt
	global_load_dword v73, v[40:41], off sc1 nt
	global_load_dword v74, v[42:43], off sc1 nt
	global_load_dword v75, v[44:45], off sc1 nt
	global_load_dword v76, v[46:47], off sc1 nt
	global_load_dword v77, v[32:33], off sc1 nt
	s_waitcnt vmcnt(30)
	ds_write2_b32 v18, v0, v31 offset1:66
	s_waitcnt vmcnt(28)
	ds_write2_b32 v18, v50, v51 offset0:132 offset1:198
	s_waitcnt vmcnt(26)
	ds_write2_b32 v24, v52, v53 offset0:8 offset1:74
	s_waitcnt vmcnt(24)
	ds_write2_b32 v24, v54, v55 offset0:140 offset1:206
	s_waitcnt vmcnt(22)
	ds_write2_b32 v25, v56, v57 offset0:16 offset1:82
	s_waitcnt vmcnt(20)
	ds_write2_b32 v25, v58, v59 offset0:148 offset1:214
	s_waitcnt vmcnt(18)
	ds_write2_b32 v26, v60, v61 offset0:24 offset1:90
	s_waitcnt vmcnt(16)
	ds_write2_b32 v26, v62, v63 offset0:156 offset1:222
	s_waitcnt vmcnt(14)
	ds_write2_b32 v27, v64, v65 offset0:32 offset1:98
	s_waitcnt vmcnt(12)
	ds_write2_b32 v27, v66, v67 offset0:164 offset1:230
	s_waitcnt vmcnt(10)
	ds_write2_b32 v28, v68, v69 offset0:40 offset1:106
	s_waitcnt vmcnt(8)
	ds_write2_b32 v28, v70, v71 offset0:172 offset1:238
	s_waitcnt vmcnt(6)
	ds_write2_b32 v29, v48, v49 offset0:48 offset1:114
	s_waitcnt vmcnt(4)
	ds_write2_b32 v29, v72, v73 offset0:180 offset1:246
	s_waitcnt vmcnt(2)
	ds_write2_b32 v30, v74, v75 offset0:56 offset1:122
	s_waitcnt vmcnt(0)
	ds_write2_b32 v30, v76, v77 offset0:188 offset1:254
	s_waitcnt lgkmcnt(0)
	ds_read2_b32 v[36:37], v20 offset0:33 offset1:41
	ds_read2_b32 v[38:39], v20 offset1:8
	ds_read2_b32 v[40:41], v20 offset0:66 offset1:74
	ds_read2_b32 v[42:43], v20 offset0:99 offset1:107
	ds_read2_b32 v[44:45], v20 offset0:132 offset1:140
	ds_read2_b32 v[46:47], v20 offset0:165 offset1:173
	ds_read2_b32 v[48:49], v20 offset0:198 offset1:206
	ds_read2_b32 v[50:51], v20 offset0:231 offset1:239
	v_lshl_add_u64 v[52:53], v[8:9], 0, s[0:1]
	v_lshlrev_b32_e32 v0, 11, v17
	s_waitcnt lgkmcnt(6)
	v_cvt_pk_bf16_f32 v32, v38, v36
	s_waitcnt lgkmcnt(4)
	v_cvt_pk_bf16_f32 v33, v40, v42
	s_waitcnt lgkmcnt(2)
	v_cvt_pk_bf16_f32 v34, v44, v46
	s_waitcnt lgkmcnt(0)
	v_cvt_pk_bf16_f32 v35, v48, v50
	v_lshl_add_u64 v[54:55], v[52:53], 0, v[0:1]
	global_store_dwordx4 v[54:55], v[32:35], off
	v_lshlrev_b32_e32 v0, 11, v16
	v_lshl_add_u64 v[16:17], v[52:53], 0, v[0:1]
	v_cvt_pk_bf16_f32 v32, v39, v37
	v_cvt_pk_bf16_f32 v33, v41, v43
	v_cvt_pk_bf16_f32 v34, v45, v47
	v_cvt_pk_bf16_f32 v35, v49, v51
	ds_read2_b32 v[36:37], v20 offset0:49 offset1:57
	ds_read2_b32 v[38:39], v20 offset0:16 offset1:24
	ds_read2_b32 v[40:41], v20 offset0:82 offset1:90
	ds_read2_b32 v[42:43], v20 offset0:115 offset1:123
	ds_read2_b32 v[44:45], v20 offset0:148 offset1:156
	ds_read2_b32 v[46:47], v20 offset0:181 offset1:189
	ds_read2_b32 v[48:49], v20 offset0:214 offset1:222
	ds_read2_b32 v[50:51], v20 offset0:247 offset1:255
	v_lshlrev_b32_e32 v0, 11, v15
	global_store_dwordx4 v[16:17], v[32:35], off
	v_lshl_add_u64 v[16:17], v[52:53], 0, v[0:1]
	v_lshlrev_b32_e32 v0, 11, v14
	s_waitcnt lgkmcnt(6)
	v_cvt_pk_bf16_f32 v32, v38, v36
	s_waitcnt lgkmcnt(4)
	v_cvt_pk_bf16_f32 v33, v40, v42
	s_waitcnt lgkmcnt(2)
	v_cvt_pk_bf16_f32 v34, v44, v46
	s_waitcnt lgkmcnt(0)
	v_cvt_pk_bf16_f32 v35, v48, v50
	global_store_dwordx4 v[16:17], v[32:35], off
	v_lshl_add_u64 v[14:15], v[52:53], 0, v[0:1]
	s_nop 0
	v_cvt_pk_bf16_f32 v32, v39, v37
	v_cvt_pk_bf16_f32 v33, v41, v43
	v_cvt_pk_bf16_f32 v34, v45, v47
	v_cvt_pk_bf16_f32 v35, v49, v51
	global_store_dwordx4 v[14:15], v[32:35], off
	s_waitcnt lgkmcnt(0)

.LBB0_855:
	s_andn2_b64 vcc, exec, s[4:5]
	s_cbranch_vccnz .LBB0_848
	s_ashr_i32 s0, s8, 31
	s_lshr_b32 s0, s0, 25
	s_add_i32 s0, s8, s0
	s_ashr_i32 s0, s0, 7
	s_lshl_b32 s6, s0, 6
	s_lshl_b32 s0, s0, 12
	s_sub_i32 s4, s9, s0
	v_or_b32_e32 v16, s6, v229
	s_ashr_i32 s5, s4, 31
	v_ashrrev_i32_e32 v17, 31, v16
	v_lshl_add_u64 v[14:15], s[4:5], 2, v[10:11]
	v_lshlrev_b64 v[32:33], 14, v[16:17]
	v_lshl_add_u64 v[32:33], v[14:15], 0, v[32:33]
	global_load_dword v0, v[32:33], off sc1 nt
	v_lshl_add_u64 v[32:33], v[16:17], 2, s[2:3]
	global_load_dword v31, v[32:33], off sc1 nt
	v_or_b32_e32 v32, 2, v16
	v_ashrrev_i32_e32 v33, 31, v32
	v_lshlrev_b64 v[34:35], 14, v[32:33]
	v_lshl_add_u64 v[32:33], v[32:33], 2, s[2:3]
	global_load_dword v37, v[32:33], off sc1 nt
	v_or_b32_e32 v32, 4, v16
	v_lshl_add_u64 v[34:35], v[14:15], 0, v[34:35]
	v_ashrrev_i32_e32 v33, 31, v32
	global_load_dword v36, v[34:35], off sc1 nt
	v_lshlrev_b64 v[34:35], 14, v[32:33]
	v_lshl_add_u64 v[32:33], v[32:33], 2, s[2:3]
	global_load_dword v39, v[32:33], off sc1 nt
	v_or_b32_e32 v32, 6, v16
	v_lshl_add_u64 v[34:35], v[14:15], 0, v[34:35]
	v_ashrrev_i32_e32 v33, 31, v32
	global_load_dword v38, v[34:35], off sc1 nt
	v_lshlrev_b64 v[34:35], 14, v[32:33]
	v_lshl_add_u64 v[32:33], v[32:33], 2, s[2:3]
	global_load_dword v41, v[32:33], off sc1 nt
	v_or_b32_e32 v32, 8, v16
	v_lshl_add_u64 v[34:35], v[14:15], 0, v[34:35]
	v_ashrrev_i32_e32 v33, 31, v32
	global_load_dword v40, v[34:35], off sc1 nt
	v_lshlrev_b64 v[34:35], 14, v[32:33]
	v_lshl_add_u64 v[32:33], v[32:33], 2, s[2:3]
	global_load_dword v43, v[32:33], off sc1 nt
	v_or_b32_e32 v32, 10, v16
	v_lshl_add_u64 v[34:35], v[14:15], 0, v[34:35]
	v_ashrrev_i32_e32 v33, 31, v32
	global_load_dword v42, v[34:35], off sc1 nt
	v_lshlrev_b64 v[34:35], 14, v[32:33]
	v_lshl_add_u64 v[32:33], v[32:33], 2, s[2:3]
	global_load_dword v45, v[32:33], off sc1 nt
	v_or_b32_e32 v32, 12, v16
	v_lshl_add_u64 v[34:35], v[14:15], 0, v[34:35]
	v_ashrrev_i32_e32 v33, 31, v32
	global_load_dword v44, v[34:35], off sc1 nt
	v_lshlrev_b64 v[34:35], 14, v[32:33]
	v_lshl_add_u64 v[32:33], v[32:33], 2, s[2:3]
	global_load_dword v47, v[32:33], off sc1 nt
	v_or_b32_e32 v32, 14, v16
	v_lshl_add_u64 v[34:35], v[14:15], 0, v[34:35]
	v_ashrrev_i32_e32 v33, 31, v32
	global_load_dword v46, v[34:35], off sc1 nt
	v_lshlrev_b64 v[34:35], 14, v[32:33]
	v_lshl_add_u64 v[32:33], v[32:33], 2, s[2:3]
	global_load_dword v49, v[32:33], off sc1 nt
	v_or_b32_e32 v32, 16, v16
	v_lshl_add_u64 v[34:35], v[14:15], 0, v[34:35]
	v_ashrrev_i32_e32 v33, 31, v32
	global_load_dword v48, v[34:35], off sc1 nt
	v_lshlrev_b64 v[34:35], 14, v[32:33]
	v_lshl_add_u64 v[32:33], v[32:33], 2, s[2:3]
	global_load_dword v51, v[32:33], off sc1 nt
	v_or_b32_e32 v32, 18, v16
	v_lshl_add_u64 v[34:35], v[14:15], 0, v[34:35]
	v_ashrrev_i32_e32 v33, 31, v32
	global_load_dword v50, v[34:35], off sc1 nt
	v_lshlrev_b64 v[34:35], 14, v[32:33]
	v_lshl_add_u64 v[32:33], v[32:33], 2, s[2:3]
	global_load_dword v53, v[32:33], off sc1 nt
	v_or_b32_e32 v32, 20, v16
	v_lshl_add_u64 v[34:35], v[14:15], 0, v[34:35]
	v_ashrrev_i32_e32 v33, 31, v32
	global_load_dword v52, v[34:35], off sc1 nt
	v_lshlrev_b64 v[34:35], 14, v[32:33]
	v_lshl_add_u64 v[32:33], v[32:33], 2, s[2:3]
	global_load_dword v55, v[32:33], off sc1 nt
	v_or_b32_e32 v32, 22, v16
	v_lshl_add_u64 v[34:35], v[14:15], 0, v[34:35]
	v_ashrrev_i32_e32 v33, 31, v32
	global_load_dword v54, v[34:35], off sc1 nt
	v_lshlrev_b64 v[34:35], 14, v[32:33]
	v_lshl_add_u64 v[32:33], v[32:33], 2, s[2:3]
	global_load_dword v57, v[32:33], off sc1 nt
	v_or_b32_e32 v32, 24, v16
	v_lshl_add_u64 v[34:35], v[14:15], 0, v[34:35]
	v_ashrrev_i32_e32 v33, 31, v32
	global_load_dword v56, v[34:35], off sc1 nt
	v_lshlrev_b64 v[34:35], 14, v[32:33]
	v_lshl_add_u64 v[32:33], v[32:33], 2, s[2:3]
	global_load_dword v59, v[32:33], off sc1 nt
	v_or_b32_e32 v32, 26, v16
	v_lshl_add_u64 v[34:35], v[14:15], 0, v[34:35]
	v_ashrrev_i32_e32 v33, 31, v32
	global_load_dword v58, v[34:35], off sc1 nt
	v_lshlrev_b64 v[34:35], 14, v[32:33]
	v_lshl_add_u64 v[32:33], v[32:33], 2, s[2:3]
	global_load_dword v61, v[32:33], off sc1 nt
	v_or_b32_e32 v32, 28, v16
	v_lshl_add_u64 v[34:35], v[14:15], 0, v[34:35]
	v_ashrrev_i32_e32 v33, 31, v32
	global_load_dword v60, v[34:35], off sc1 nt
	v_lshlrev_b64 v[34:35], 14, v[32:33]
	v_lshl_add_u64 v[32:33], v[32:33], 2, s[2:3]
	global_load_dword v63, v[32:33], off sc1 nt
	v_or_b32_e32 v32, 30, v16
	v_lshl_add_u64 v[34:35], v[14:15], 0, v[34:35]
	v_ashrrev_i32_e32 v33, 31, v32
	global_load_dword v62, v[34:35], off sc1 nt
	v_lshlrev_b64 v[34:35], 14, v[32:33]
	v_lshl_add_u64 v[32:33], v[32:33], 2, s[2:3]
	global_load_dword v65, v[32:33], off sc1 nt
	v_or_b32_e32 v32, 32, v16
	v_lshl_add_u64 v[34:35], v[14:15], 0, v[34:35]
	v_ashrrev_i32_e32 v33, 31, v32
	global_load_dword v64, v[34:35], off sc1 nt
	v_lshlrev_b64 v[34:35], 14, v[32:33]
	v_lshl_add_u64 v[32:33], v[32:33], 2, s[2:3]
	global_load_dword v67, v[32:33], off sc1 nt
	v_or_b32_e32 v32, 34, v16
	v_lshl_add_u64 v[34:35], v[14:15], 0, v[34:35]
	v_ashrrev_i32_e32 v33, 31, v32
	global_load_dword v66, v[34:35], off sc1 nt
	v_lshlrev_b64 v[34:35], 14, v[32:33]
	v_lshl_add_u64 v[32:33], v[32:33], 2, s[2:3]
	global_load_dword v69, v[32:33], off sc1 nt
	v_or_b32_e32 v32, 36, v16
	v_lshl_add_u64 v[34:35], v[14:15], 0, v[34:35]
	v_ashrrev_i32_e32 v33, 31, v32
	global_load_dword v68, v[34:35], off sc1 nt
	v_lshlrev_b64 v[34:35], 14, v[32:33]
	v_lshl_add_u64 v[32:33], v[32:33], 2, s[2:3]
	global_load_dword v71, v[32:33], off sc1 nt
	v_or_b32_e32 v32, 38, v16
	v_lshl_add_u64 v[34:35], v[14:15], 0, v[34:35]
	v_ashrrev_i32_e32 v33, 31, v32
	global_load_dword v70, v[34:35], off sc1 nt
	v_lshlrev_b64 v[34:35], 14, v[32:33]
	v_lshl_add_u64 v[32:33], v[32:33], 2, s[2:3]
	global_load_dword v73, v[32:33], off sc1 nt
	v_or_b32_e32 v32, 40, v16
	v_lshl_add_u64 v[34:35], v[14:15], 0, v[34:35]
	v_ashrrev_i32_e32 v33, 31, v32
	global_load_dword v72, v[34:35], off sc1 nt
	v_lshlrev_b64 v[34:35], 14, v[32:33]
	v_lshl_add_u64 v[32:33], v[32:33], 2, s[2:3]
	global_load_dword v75, v[32:33], off sc1 nt
	v_or_b32_e32 v32, 42, v16
	v_lshl_add_u64 v[34:35], v[14:15], 0, v[34:35]
	v_ashrrev_i32_e32 v33, 31, v32
	global_load_dword v74, v[34:35], off sc1 nt
	v_lshlrev_b64 v[34:35], 14, v[32:33]
	v_lshl_add_u64 v[32:33], v[32:33], 2, s[2:3]
	global_load_dword v77, v[32:33], off sc1 nt
	v_or_b32_e32 v32, 44, v16
	v_lshl_add_u64 v[34:35], v[14:15], 0, v[34:35]
	v_ashrrev_i32_e32 v33, 31, v32
	global_load_dword v76, v[34:35], off sc1 nt
	v_lshlrev_b64 v[34:35], 14, v[32:33]
	v_lshl_add_u64 v[32:33], v[32:33], 2, s[2:3]
	global_load_dword v79, v[32:33], off sc1 nt
	v_or_b32_e32 v32, 46, v16
	v_lshl_add_u64 v[34:35], v[14:15], 0, v[34:35]
	v_ashrrev_i32_e32 v33, 31, v32
	global_load_dword v78, v[34:35], off sc1 nt
	v_lshlrev_b64 v[34:35], 14, v[32:33]
	v_lshl_add_u64 v[32:33], v[32:33], 2, s[2:3]
	global_load_dword v81, v[32:33], off sc1 nt
	v_or_b32_e32 v32, 48, v16
	v_lshl_add_u64 v[34:35], v[14:15], 0, v[34:35]
	v_ashrrev_i32_e32 v33, 31, v32
	global_load_dword v80, v[34:35], off sc1 nt
	v_lshlrev_b64 v[34:35], 14, v[32:33]
	v_lshl_add_u64 v[32:33], v[32:33], 2, s[2:3]
	global_load_dword v83, v[32:33], off sc1 nt
	v_or_b32_e32 v32, 50, v16
	v_lshl_add_u64 v[34:35], v[14:15], 0, v[34:35]
	v_ashrrev_i32_e32 v33, 31, v32
	global_load_dword v82, v[34:35], off sc1 nt
	v_lshlrev_b64 v[34:35], 14, v[32:33]
	v_lshl_add_u64 v[32:33], v[32:33], 2, s[2:3]
	global_load_dword v85, v[32:33], off sc1 nt
	v_or_b32_e32 v32, 52, v16
	v_lshl_add_u64 v[34:35], v[14:15], 0, v[34:35]
	v_ashrrev_i32_e32 v33, 31, v32
	global_load_dword v84, v[34:35], off sc1 nt
	v_lshlrev_b64 v[34:35], 14, v[32:33]
	v_lshl_add_u64 v[32:33], v[32:33], 2, s[2:3]
	global_load_dword v87, v[32:33], off sc1 nt
	v_or_b32_e32 v32, 54, v16
	v_lshl_add_u64 v[34:35], v[14:15], 0, v[34:35]
	v_ashrrev_i32_e32 v33, 31, v32
	global_load_dword v86, v[34:35], off sc1 nt
	v_lshlrev_b64 v[34:35], 14, v[32:33]
	v_lshl_add_u64 v[32:33], v[32:33], 2, s[2:3]
	global_load_dword v89, v[32:33], off sc1 nt
	v_or_b32_e32 v32, 56, v16
	v_lshl_add_u64 v[34:35], v[14:15], 0, v[34:35]
	v_ashrrev_i32_e32 v33, 31, v32
	global_load_dword v88, v[34:35], off sc1 nt
	v_lshlrev_b64 v[34:35], 14, v[32:33]
	v_lshl_add_u64 v[32:33], v[32:33], 2, s[2:3]
	global_load_dword v91, v[32:33], off sc1 nt
	v_or_b32_e32 v32, 58, v16
	v_lshl_add_u64 v[34:35], v[14:15], 0, v[34:35]
	v_ashrrev_i32_e32 v33, 31, v32
	global_load_dword v90, v[34:35], off sc1 nt
	v_lshlrev_b64 v[34:35], 14, v[32:33]
	v_lshl_add_u64 v[32:33], v[32:33], 2, s[2:3]
	global_load_dword v93, v[32:33], off sc1 nt
	v_or_b32_e32 v32, 60, v16
	v_lshl_add_u64 v[34:35], v[14:15], 0, v[34:35]
	v_ashrrev_i32_e32 v33, 31, v32
	global_load_dword v92, v[34:35], off sc1 nt
	v_lshlrev_b64 v[34:35], 14, v[32:33]
	v_or_b32_e32 v16, 62, v16
	v_lshl_add_u64 v[34:35], v[14:15], 0, v[34:35]
	v_lshl_add_u64 v[32:33], v[32:33], 2, s[2:3]
	v_ashrrev_i32_e32 v17, 31, v16
	global_load_dword v34, v[34:35], off sc1 nt
	s_waitcnt vmcnt(59)
	v_mul_f32_e32 v0, v0, v31
	global_load_dword v35, v[32:33], off sc1 nt
	v_lshlrev_b64 v[32:33], 14, v[16:17]
	v_lshl_add_u64 v[14:15], v[14:15], 0, v[32:33]
	global_load_dword v32, v[14:15], off sc1 nt
	v_lshl_add_u64 v[14:15], v[16:17], 2, s[2:3]
	global_load_dword v14, v[14:15], off sc1 nt
	s_waitcnt vmcnt(60)
	v_mul_f32_e32 v15, v36, v37
	ds_write2_b32 v18, v0, v15 offset1:66
	s_waitcnt vmcnt(58)
	v_mul_f32_e32 v0, v38, v39
	s_waitcnt vmcnt(56)
	v_mul_f32_e32 v15, v40, v41
	ds_write2_b32 v18, v0, v15 offset0:132 offset1:198
	s_waitcnt vmcnt(54)
	v_mul_f32_e32 v0, v42, v43
	s_waitcnt vmcnt(52)
	v_mul_f32_e32 v15, v44, v45
	ds_write2_b32 v24, v0, v15 offset0:8 offset1:74
	s_waitcnt vmcnt(50)
	v_mul_f32_e32 v0, v46, v47
	s_waitcnt vmcnt(48)
	v_mul_f32_e32 v15, v48, v49
	ds_write2_b32 v24, v0, v15 offset0:140 offset1:206
	s_waitcnt vmcnt(46)
	v_mul_f32_e32 v0, v50, v51
	s_waitcnt vmcnt(44)
	v_mul_f32_e32 v15, v52, v53
	ds_write2_b32 v25, v0, v15 offset0:16 offset1:82
	s_waitcnt vmcnt(42)
	v_mul_f32_e32 v0, v54, v55
	s_waitcnt vmcnt(40)
	v_mul_f32_e32 v15, v56, v57
	ds_write2_b32 v25, v0, v15 offset0:148 offset1:214
	s_waitcnt vmcnt(38)
	v_mul_f32_e32 v0, v58, v59
	s_waitcnt vmcnt(36)
	v_mul_f32_e32 v15, v60, v61
	ds_write2_b32 v26, v0, v15 offset0:24 offset1:90
	s_waitcnt vmcnt(34)
	v_mul_f32_e32 v0, v62, v63
	s_waitcnt vmcnt(32)
	v_mul_f32_e32 v15, v64, v65
	ds_write2_b32 v26, v0, v15 offset0:156 offset1:222
	s_waitcnt vmcnt(30)
	v_mul_f32_e32 v0, v66, v67
	s_waitcnt vmcnt(28)
	v_mul_f32_e32 v15, v68, v69
	ds_write2_b32 v27, v0, v15 offset0:32 offset1:98
	s_waitcnt vmcnt(26)
	v_mul_f32_e32 v0, v70, v71
	s_waitcnt vmcnt(24)
	v_mul_f32_e32 v15, v72, v73
	ds_write2_b32 v27, v0, v15 offset0:164 offset1:230
	s_waitcnt vmcnt(22)
	v_mul_f32_e32 v0, v74, v75
	s_waitcnt vmcnt(20)
	v_mul_f32_e32 v15, v76, v77
	ds_write2_b32 v28, v0, v15 offset0:40 offset1:106
	s_waitcnt vmcnt(18)
	v_mul_f32_e32 v0, v78, v79
	s_waitcnt vmcnt(16)
	v_mul_f32_e32 v15, v80, v81
	ds_write2_b32 v28, v0, v15 offset0:172 offset1:238
	s_waitcnt vmcnt(14)
	v_mul_f32_e32 v0, v82, v83
	v_add_u32_e32 v50, s4, v19
	s_ashr_i32 s7, s6, 31
	s_waitcnt vmcnt(12)
	v_mul_f32_e32 v15, v84, v85
	ds_write2_b32 v29, v0, v15 offset0:48 offset1:114
	v_ashrrev_i32_e32 v51, 31, v50
	v_lshl_add_u64 v[48:49], s[6:7], 1, v[12:13]
	v_lshlrev_b64 v[52:53], 11, v[50:51]
	v_lshl_add_u64 v[52:53], v[48:49], 0, v[52:53]
	s_waitcnt vmcnt(10)
	v_mul_f32_e32 v0, v86, v87
	s_waitcnt vmcnt(8)
	v_mul_f32_e32 v15, v88, v89
	ds_write2_b32 v29, v0, v15 offset0:180 offset1:246
	s_waitcnt vmcnt(6)
	v_mul_f32_e32 v0, v90, v91
	s_waitcnt vmcnt(4)
	v_mul_f32_e32 v15, v92, v93
	ds_write2_b32 v30, v0, v15 offset0:56 offset1:122
	s_waitcnt vmcnt(2)
	v_mul_f32_e32 v0, v34, v35
	s_waitcnt vmcnt(0)
	v_mul_f32_e32 v14, v32, v14
	ds_write2_b32 v30, v0, v14 offset0:188 offset1:254
	s_waitcnt lgkmcnt(0)
	ds_read2_b32 v[32:33], v20 offset0:33 offset1:41
	ds_read2_b32 v[34:35], v20 offset1:8
	ds_read2_b32 v[36:37], v20 offset0:66 offset1:74
	ds_read2_b32 v[38:39], v20 offset0:99 offset1:107
	ds_read2_b32 v[40:41], v20 offset0:132 offset1:140
	ds_read2_b32 v[42:43], v20 offset0:165 offset1:173
	ds_read2_b32 v[44:45], v20 offset0:198 offset1:206
	ds_read2_b32 v[46:47], v20 offset0:231 offset1:239
	s_waitcnt lgkmcnt(6)
	v_cvt_pk_bf16_f32 v14, v34, v32
	s_waitcnt lgkmcnt(4)
	v_cvt_pk_bf16_f32 v15, v36, v38
	s_waitcnt lgkmcnt(2)
	v_cvt_pk_bf16_f32 v16, v40, v42
	v_add_u32_e32 v32, 8, v50
	s_waitcnt lgkmcnt(0)
	v_cvt_pk_bf16_f32 v17, v44, v46
	global_store_dwordx4 v[52:53], v[14:17], off
	s_nop 1
	v_cvt_pk_bf16_f32 v14, v35, v33
	v_ashrrev_i32_e32 v33, 31, v32
	v_cvt_pk_bf16_f32 v15, v37, v39
	v_cvt_pk_bf16_f32 v16, v41, v43
	v_cvt_pk_bf16_f32 v17, v45, v47
	v_lshlrev_b64 v[32:33], 11, v[32:33]
	ds_read2_b32 v[34:35], v20 offset0:49 offset1:57
	ds_read2_b32 v[36:37], v20 offset0:16 offset1:24
	ds_read2_b32 v[38:39], v20 offset0:82 offset1:90
	ds_read2_b32 v[40:41], v20 offset0:115 offset1:123
	ds_read2_b32 v[42:43], v20 offset0:148 offset1:156
	ds_read2_b32 v[44:45], v20 offset0:181 offset1:189
	ds_read2_b32 v[46:47], v20 offset0:214 offset1:222
	ds_read2_b32 v[52:53], v20 offset0:247 offset1:255
	v_lshl_add_u64 v[32:33], v[48:49], 0, v[32:33]
	global_store_dwordx4 v[32:33], v[14:17], off
	v_add_u32_e32 v32, 16, v50
	v_ashrrev_i32_e32 v33, 31, v32
	v_lshlrev_b64 v[32:33], 11, v[32:33]
	s_waitcnt lgkmcnt(6)
	v_cvt_pk_bf16_f32 v14, v36, v34
	s_waitcnt lgkmcnt(4)
	v_cvt_pk_bf16_f32 v15, v38, v40
	s_waitcnt lgkmcnt(2)
	v_cvt_pk_bf16_f32 v16, v42, v44
	s_waitcnt lgkmcnt(0)
	v_cvt_pk_bf16_f32 v17, v46, v52
	v_lshl_add_u64 v[32:33], v[48:49], 0, v[32:33]
	global_store_dwordx4 v[32:33], v[14:17], off
	v_add_u32_e32 v32, 24, v50
	v_ashrrev_i32_e32 v33, 31, v32
	v_lshlrev_b64 v[32:33], 11, v[32:33]
	v_cvt_pk_bf16_f32 v14, v37, v35
	v_cvt_pk_bf16_f32 v15, v39, v41
	v_cvt_pk_bf16_f32 v16, v43, v45
	v_cvt_pk_bf16_f32 v17, v47, v53
	v_lshl_add_u64 v[32:33], v[48:49], 0, v[32:33]
	global_store_dwordx4 v[32:33], v[14:17], off
	s_waitcnt lgkmcnt(0)
	s_branch .LBB0_848
